# step4 + software-pipelined residual loads in the in-place LN-residual epilogues (loads into alternate registers, counted vmcnt so waits no longer cover the preceding store)
# speedup vs baseline: 1.0109x; 1.0014x over previous
.LBB0_858:
	v_lshl_add_u32 v128, s84, 8, v224
	v_ashrrev_i32_e32 v129, 31, v128
	v_lshlrev_b64 v[164:165], 3, v[128:129]
	v_lshl_add_u64 v[130:131], s[20:21], 0, v[164:165]
	global_load_dwordx2 v[186:187], v[130:131], off
	v_lshl_or_b32 v130, s81, 8, v228
	v_ashrrev_i32_e32 v131, 31, v130
	v_lshlrev_b64 v[132:133], 12, v[128:129]
	v_lshl_add_u64 v[132:133], s[16:17], 0, v[132:133]
	v_lshlrev_b64 v[178:179], 1, v[130:131]
	v_lshl_add_u64 v[176:177], v[132:133], 0, v[178:179]
	global_load_dwordx4 v[192:195], v[176:177], off
	v_or_b32_e32 v196, 16, v128
	v_or_b32_e32 v218, 32, v128
	v_or_b32_e32 v198, 48, v128
	v_add_u32_e32 v204, 0x80, v128
	v_add_u32_e32 v208, 0x90, v128
	v_add_u32_e32 v184, 0xa0, v128
	v_add_u32_e32 v180, 0xb0, v128
	v_lshlrev_b64 v[128:129], 2, v[130:131]
	v_lshl_add_u64 v[188:189], s[64:65], 0, v[128:129]
	v_lshl_add_u64 v[190:191], s[66:67], 0, v[128:129]
	global_load_dwordx4 v[128:131], v[188:189], off offset:16
	global_load_dwordx4 v[136:139], v[188:189], off
	global_load_dwordx4 v[132:135], v[190:191], off offset:16
	global_load_dwordx4 v[140:143], v[190:191], off
	v_ashrrev_i32_e32 v197, 31, v196
	v_ashrrev_i32_e32 v219, 31, v218
	v_ashrrev_i32_e32 v199, 31, v198
	v_ashrrev_i32_e32 v205, 31, v204
	v_ashrrev_i32_e32 v209, 31, v208
	v_ashrrev_i32_e32 v185, 31, v184
	v_ashrrev_i32_e32 v181, 31, v180
	v_lshlrev_b64 v[174:175], 3, v[196:197]
	v_lshlrev_b64 v[172:173], 3, v[218:219]
	v_lshlrev_b64 v[170:171], 3, v[198:199]
	v_lshlrev_b64 v[168:169], 3, v[204:205]
	v_lshlrev_b64 v[166:167], 3, v[208:209]
	v_lshlrev_b64 v[162:163], 3, v[184:185]
	v_lshlrev_b64 v[160:161], 3, v[180:181]
	v_lshl_add_u64 v[182:183], s[20:21], 0, v[174:175]
	v_lshl_add_u64 v[200:201], s[20:21], 0, v[172:173]
	v_lshl_add_u64 v[202:203], s[20:21], 0, v[170:171]
	v_lshl_add_u64 v[210:211], s[20:21], 0, v[168:169]
	v_lshl_add_u64 v[212:213], s[20:21], 0, v[166:167]
	v_lshl_add_u64 v[214:215], s[20:21], 0, v[162:163]
	v_lshl_add_u64 v[216:217], s[20:21], 0, v[160:161]
	global_load_dwordx2 v[234:235], v[182:183], off
	s_nop 0
	global_load_dwordx2 v[200:201], v[200:201], off
	s_nop 0
	global_load_dwordx2 v[206:207], v[202:203], off
	s_nop 0
	global_load_dwordx2 v[210:211], v[210:211], off
	s_nop 0
	global_load_dwordx2 v[212:213], v[212:213], off
	s_nop 0
	global_load_dwordx2 v[182:183], v[214:215], off
	global_load_dwordx2 v[202:203], v[216:217], off
	v_lshlrev_b64 v[198:199], 12, v[198:199]
	v_lshl_add_u64 v[198:199], s[16:17], 0, v[198:199]
	v_lshl_add_u64 v[198:199], v[198:199], 0, v[178:179]
	v_lshlrev_b64 v[204:205], 12, v[204:205]
	v_lshl_add_u64 v[204:205], s[16:17], 0, v[204:205]
	v_lshl_add_u64 v[204:205], v[204:205], 0, v[178:179]
	v_lshlrev_b64 v[208:209], 12, v[208:209]
	v_lshl_add_u64 v[208:209], s[16:17], 0, v[208:209]
	v_lshl_add_u64 v[208:209], v[208:209], 0, v[178:179]
	v_lshlrev_b64 v[184:185], 12, v[184:185]
	v_lshl_add_u64 v[184:185], s[16:17], 0, v[184:185]
	v_lshlrev_b64 v[180:181], 12, v[180:181]
	v_lshl_add_u64 v[180:181], s[16:17], 0, v[180:181]
	s_waitcnt vmcnt(0)
	v_pk_mul_f32 v[186:187], v[186:187], s[34:35] op_sel:[1,0] op_sel_hi:[0,0]
	v_fma_f32 v186, -v187, v187, v186
	v_max_f32_e32 v186, 0, v186
	v_add_f32_e32 v186, 0x3727c5ac, v186
	v_cmp_gt_f32_e32 vcc, s78, v186
	v_lshlrev_b32_e32 v214, 16, v192
	v_and_b32_e32 v192, 0xffff0000, v192
	v_lshlrev_b32_e32 v215, 16, v193
	v_and_b32_e32 v216, 0xffff0000, v193
	v_sub_f32_e32 v193, v192, v187
	v_sub_f32_e32 v192, v214, v187
	v_mul_f32_e32 v214, 0x4f800000, v186
	v_cndmask_b32_e32 v186, v186, v214, vcc
	v_lshlrev_b32_e32 v236, 16, v195
	v_and_b32_e32 v237, 0xffff0000, v195
	v_sub_f32_e32 v195, v216, v187
	v_sqrt_f32_e32 v216, v186
	v_and_b32_e32 v233, 0xffff0000, v194
	v_lshlrev_b32_e32 v217, 16, v194
	v_sub_f32_e32 v194, v215, v187
	v_sub_f32_e32 v215, v233, v187
	v_add_u32_e32 v233, -1, v216
	v_sub_f32_e32 v214, v217, v187
	v_sub_f32_e32 v217, v237, v187
	v_add_u32_e32 v237, 1, v216
	v_fma_f32 v238, -v233, v216, v186
	v_fma_f32 v239, -v237, v216, v186
	v_cmp_ge_f32_e64 s[0:1], 0, v238
	v_pk_mul_f32 v[200:201], v[200:201], s[34:35] op_sel:[1,0] op_sel_hi:[0,0]
	s_nop 0
	v_cndmask_b32_e64 v216, v216, v233, s[0:1]
	v_cmp_lt_f32_e64 s[0:1], 0, v239
	v_fma_f32 v200, -v201, v201, v200
	v_max_f32_e32 v200, 0, v200
	v_cndmask_b32_e64 v216, v216, v237, s[0:1]
	v_mul_f32_e32 v233, 0x37800000, v216
	v_cndmask_b32_e32 v216, v216, v233, vcc
	v_cmp_class_f32_e32 vcc, v186, v232
	v_add_f32_e32 v200, 0x3727c5ac, v200
	v_pk_mul_f32 v[206:207], v[206:207], s[34:35] op_sel:[1,0] op_sel_hi:[0,0]
	v_cndmask_b32_e32 v186, v216, v186, vcc
	v_div_scale_f32 v233, s[0:1], v186, v186, 1.0
	v_rcp_f32_e32 v237, v233
	v_sub_f32_e32 v216, v236, v187
	v_div_scale_f32 v236, vcc, 1.0, v186, 1.0
	v_fma_f32 v238, -v233, v237, 1.0
	v_fmac_f32_e32 v237, v238, v237
	v_mul_f32_e32 v238, v236, v237
	v_fma_f32 v239, -v233, v238, v236
	v_fmac_f32_e32 v238, v239, v237
	v_fma_f32 v233, -v233, v238, v236
	v_div_fmas_f32 v233, v233, v237, v238
	v_div_fixup_f32 v186, v233, v186, 1.0
	v_pk_mul_f32 v[194:195], v[186:187], v[194:195] op_sel_hi:[0,1]
	v_pk_mul_f32 v[192:193], v[186:187], v[192:193] op_sel_hi:[0,1]
	v_pk_mul_f32 v[216:217], v[186:187], v[216:217] op_sel_hi:[0,1]
	v_pk_mul_f32 v[214:215], v[186:187], v[214:215] op_sel_hi:[0,1]
	v_pk_fma_f32 v[192:193], v[136:137], v[192:193], v[140:141]
	v_pk_fma_f32 v[194:195], v[138:139], v[194:195], v[142:143]
	v_pk_fma_f32 v[214:215], v[128:129], v[214:215], v[132:133]
	v_pk_fma_f32 v[216:217], v[130:131], v[216:217], v[134:135]
	v_pk_fma_f32 v[126:127], v[194:195], s[36:37], v[126:127] op_sel_hi:[1,0,1]
	v_pk_fma_f32 v[124:125], v[192:193], s[36:37], v[124:125] op_sel_hi:[1,0,1]
	v_pk_fma_f32 v[122:123], v[216:217], s[36:37], v[122:123] op_sel_hi:[1,0,1]
	v_pk_fma_f32 v[120:121], v[214:215], s[36:37], v[120:121] op_sel_hi:[1,0,1]
	v_cvt_pk_bf16_f32 v192, v124, v125
	v_cvt_pk_bf16_f32 v193, v126, v127
	v_cvt_pk_bf16_f32 v194, v120, v121
	v_cvt_pk_bf16_f32 v195, v122, v123
	global_store_dwordx4 v[176:177], v[192:195], off
	v_fma_f32 v206, -v207, v207, v206
	v_max_f32_e32 v206, 0, v206
	v_lshlrev_b64 v[192:193], 12, v[196:197]
	v_lshl_add_u64 v[192:193], s[16:17], 0, v[192:193]
	v_lshl_add_u64 v[192:193], v[192:193], 0, v[178:179]
	global_load_dwordx4 v[214:217], v[192:193], off
	v_pk_mul_f32 v[196:197], v[234:235], s[34:35] op_sel:[1,0] op_sel_hi:[0,0]
	v_fma_f32 v194, -v197, v197, v196
	v_max_f32_e32 v194, 0, v194
	v_add_f32_e32 v194, 0x3727c5ac, v194
	v_mul_f32_e32 v195, 0x4f800000, v194
	v_cmp_gt_f32_e32 vcc, s78, v194
	v_add_f32_e32 v206, 0x3727c5ac, v206
	v_pk_mul_f32 v[210:211], v[210:211], s[34:35] op_sel:[1,0] op_sel_hi:[0,0]
	v_cndmask_b32_e32 v196, v194, v195, vcc
	v_sqrt_f32_e32 v233, v196
	v_lshlrev_b64 v[194:195], 12, v[218:219]
	v_lshl_add_u64 v[194:195], s[16:17], 0, v[194:195]
	v_lshl_add_u64 v[194:195], v[194:195], 0, v[178:179]
	v_add_u32_e32 v218, -1, v233
	v_add_u32_e32 v219, 1, v233
	v_fma_f32 v234, -v218, v233, v196
	v_fma_f32 v235, -v219, v233, v196
	v_cmp_ge_f32_e64 s[0:1], 0, v234
	v_fma_f32 v210, -v211, v211, v210
	v_max_f32_e32 v210, 0, v210
	v_cndmask_b32_e64 v218, v233, v218, s[0:1]
	v_cmp_lt_f32_e64 s[0:1], 0, v235
	v_add_f32_e32 v210, 0x3727c5ac, v210
	v_pk_mul_f32 v[202:203], v[202:203], s[34:35] op_sel:[1,0] op_sel_hi:[0,0]
	v_cndmask_b32_e64 v218, v218, v219, s[0:1]
	v_mul_f32_e32 v219, 0x37800000, v218
	v_cndmask_b32_e32 v218, v218, v219, vcc
	v_cmp_class_f32_e32 vcc, v196, v232
	s_waitcnt vmcnt(0)
	v_lshlrev_b32_e32 v236, 16, v217
	v_cndmask_b32_e32 v196, v218, v196, vcc
	v_div_scale_f32 v218, s[0:1], v196, v196, 1.0
	v_rcp_f32_e32 v219, v218
	v_div_scale_f32 v233, vcc, 1.0, v196, 1.0
	v_and_b32_e32 v237, 0xffff0000, v217
	v_fma_f32 v234, -v218, v219, 1.0
	v_fmac_f32_e32 v219, v234, v219
	v_mul_f32_e32 v234, v233, v219
	v_fma_f32 v235, -v218, v234, v233
	v_fmac_f32_e32 v234, v235, v219
	v_fma_f32 v218, -v218, v234, v233
	v_div_fmas_f32 v218, v218, v219, v234
	v_div_fixup_f32 v196, v218, v196, 1.0
	v_lshlrev_b32_e32 v218, 16, v214
	v_and_b32_e32 v214, 0xffff0000, v214
	v_lshlrev_b32_e32 v219, 16, v215
	v_and_b32_e32 v233, 0xffff0000, v215
	v_lshlrev_b32_e32 v234, 16, v216
	v_and_b32_e32 v235, 0xffff0000, v216
	v_sub_f32_e32 v215, v214, v197
	v_sub_f32_e32 v214, v218, v197
	v_sub_f32_e32 v217, v233, v197
	v_sub_f32_e32 v216, v219, v197
	v_sub_f32_e32 v219, v235, v197
	v_sub_f32_e32 v218, v234, v197
	v_sub_f32_e32 v235, v237, v197
	v_sub_f32_e32 v234, v236, v197
	v_pk_mul_f32 v[216:217], v[196:197], v[216:217] op_sel_hi:[0,1]
	v_pk_mul_f32 v[214:215], v[196:197], v[214:215] op_sel_hi:[0,1]
	v_pk_mul_f32 v[234:235], v[196:197], v[234:235] op_sel_hi:[0,1]
	v_pk_mul_f32 v[218:219], v[196:197], v[218:219] op_sel_hi:[0,1]
	v_pk_fma_f32 v[214:215], v[136:137], v[214:215], v[140:141]
	v_pk_fma_f32 v[216:217], v[138:139], v[216:217], v[142:143]
	v_pk_fma_f32 v[218:219], v[128:129], v[218:219], v[132:133]
	v_pk_fma_f32 v[234:235], v[130:131], v[234:235], v[134:135]
	v_pk_fma_f32 v[118:119], v[216:217], s[36:37], v[118:119] op_sel_hi:[1,0,1]
	v_pk_fma_f32 v[116:117], v[214:215], s[36:37], v[116:117] op_sel_hi:[1,0,1]
	v_pk_fma_f32 v[114:115], v[234:235], s[36:37], v[114:115] op_sel_hi:[1,0,1]
	v_pk_fma_f32 v[112:113], v[218:219], s[36:37], v[112:113] op_sel_hi:[1,0,1]
	v_cvt_pk_bf16_f32 v214, v116, v117
	v_cvt_pk_bf16_f32 v215, v118, v119
	v_cvt_pk_bf16_f32 v216, v112, v113
	v_cvt_pk_bf16_f32 v217, v114, v115
	global_store_dwordx4 v[192:193], v[214:217], off
	global_load_dwordx4 v[214:217], v[194:195], off
	v_mul_f32_e32 v218, 0x4f800000, v200
	v_cmp_gt_f32_e32 vcc, s78, v200
	s_waitcnt vmcnt(0)
	v_lshlrev_b32_e32 v236, 16, v217
	v_cndmask_b32_e32 v200, v200, v218, vcc
	v_sqrt_f32_e32 v218, v200
	v_and_b32_e32 v237, 0xffff0000, v217
	v_add_u32_e32 v219, -1, v218
	v_add_u32_e32 v233, 1, v218
	v_fma_f32 v234, -v219, v218, v200
	v_fma_f32 v235, -v233, v218, v200
	v_cmp_ge_f32_e64 s[0:1], 0, v234
	s_nop 1
	v_cndmask_b32_e64 v218, v218, v219, s[0:1]
	v_cmp_lt_f32_e64 s[0:1], 0, v235
	s_nop 1
	v_cndmask_b32_e64 v218, v218, v233, s[0:1]
	v_mul_f32_e32 v219, 0x37800000, v218
	v_cndmask_b32_e32 v218, v218, v219, vcc
	v_cmp_class_f32_e32 vcc, v200, v232
	s_nop 1
	v_cndmask_b32_e32 v200, v218, v200, vcc
	v_div_scale_f32 v218, s[0:1], v200, v200, 1.0
	v_rcp_f32_e32 v219, v218
	v_div_scale_f32 v233, vcc, 1.0, v200, 1.0
	v_fma_f32 v234, -v218, v219, 1.0
	v_fmac_f32_e32 v219, v234, v219
	v_mul_f32_e32 v234, v233, v219
	v_fma_f32 v235, -v218, v234, v233
	v_fmac_f32_e32 v234, v235, v219
	v_fma_f32 v218, -v218, v234, v233
	v_div_fmas_f32 v218, v218, v219, v234
	v_div_fixup_f32 v200, v218, v200, 1.0
	v_lshlrev_b32_e32 v218, 16, v214
	v_and_b32_e32 v214, 0xffff0000, v214
	v_lshlrev_b32_e32 v219, 16, v215
	v_and_b32_e32 v233, 0xffff0000, v215
	v_lshlrev_b32_e32 v234, 16, v216
	v_and_b32_e32 v235, 0xffff0000, v216
	v_sub_f32_e32 v215, v214, v201
	v_sub_f32_e32 v214, v218, v201
	v_sub_f32_e32 v217, v233, v201
	v_sub_f32_e32 v216, v219, v201
	v_sub_f32_e32 v219, v235, v201
	v_sub_f32_e32 v218, v234, v201
	v_sub_f32_e32 v235, v237, v201
	v_sub_f32_e32 v234, v236, v201
	v_pk_mul_f32 v[216:217], v[200:201], v[216:217] op_sel_hi:[0,1]
	v_pk_mul_f32 v[214:215], v[200:201], v[214:215] op_sel_hi:[0,1]
	v_pk_mul_f32 v[234:235], v[200:201], v[234:235] op_sel_hi:[0,1]
	v_pk_mul_f32 v[218:219], v[200:201], v[218:219] op_sel_hi:[0,1]
	v_pk_fma_f32 v[214:215], v[136:137], v[214:215], v[140:141]
	v_pk_fma_f32 v[216:217], v[138:139], v[216:217], v[142:143]
	v_pk_fma_f32 v[218:219], v[128:129], v[218:219], v[132:133]
	v_pk_fma_f32 v[234:235], v[130:131], v[234:235], v[134:135]
	v_pk_fma_f32 v[110:111], v[216:217], s[36:37], v[110:111] op_sel_hi:[1,0,1]
	v_pk_fma_f32 v[108:109], v[214:215], s[36:37], v[108:109] op_sel_hi:[1,0,1]
	v_pk_fma_f32 v[106:107], v[234:235], s[36:37], v[106:107] op_sel_hi:[1,0,1]
	v_pk_fma_f32 v[104:105], v[218:219], s[36:37], v[104:105] op_sel_hi:[1,0,1]
	v_cvt_pk_bf16_f32 v214, v108, v109
	v_cvt_pk_bf16_f32 v215, v110, v111
	v_cvt_pk_bf16_f32 v216, v104, v105
	v_cvt_pk_bf16_f32 v217, v106, v107
	global_store_dwordx4 v[194:195], v[214:217], off
	global_load_dwordx4 v[214:217], v[198:199], off
	v_mul_f32_e32 v218, 0x4f800000, v206
	v_cmp_gt_f32_e32 vcc, s78, v206
	s_waitcnt vmcnt(0)
	v_lshlrev_b32_e32 v236, 16, v217
	v_cndmask_b32_e32 v206, v206, v218, vcc
	v_sqrt_f32_e32 v218, v206
	v_and_b32_e32 v237, 0xffff0000, v217
	v_add_u32_e32 v219, -1, v218
	v_add_u32_e32 v233, 1, v218
	v_fma_f32 v234, -v219, v218, v206
	v_fma_f32 v235, -v233, v218, v206
	v_cmp_ge_f32_e64 s[0:1], 0, v234
	s_nop 1
	v_cndmask_b32_e64 v218, v218, v219, s[0:1]
	v_cmp_lt_f32_e64 s[0:1], 0, v235
	s_nop 1
	v_cndmask_b32_e64 v218, v218, v233, s[0:1]
	v_mul_f32_e32 v219, 0x37800000, v218
	v_cndmask_b32_e32 v218, v218, v219, vcc
	v_cmp_class_f32_e32 vcc, v206, v232
	s_nop 1
	v_cndmask_b32_e32 v206, v218, v206, vcc
	v_div_scale_f32 v218, s[0:1], v206, v206, 1.0
	v_rcp_f32_e32 v219, v218
	v_div_scale_f32 v233, vcc, 1.0, v206, 1.0
	v_fma_f32 v234, -v218, v219, 1.0
	v_fmac_f32_e32 v219, v234, v219
	v_mul_f32_e32 v234, v233, v219
	v_fma_f32 v235, -v218, v234, v233
	v_fmac_f32_e32 v234, v235, v219
	v_fma_f32 v218, -v218, v234, v233
	v_div_fmas_f32 v218, v218, v219, v234
	v_div_fixup_f32 v206, v218, v206, 1.0
	v_lshlrev_b32_e32 v218, 16, v214
	v_and_b32_e32 v214, 0xffff0000, v214
	v_lshlrev_b32_e32 v219, 16, v215
	v_and_b32_e32 v233, 0xffff0000, v215
	v_lshlrev_b32_e32 v234, 16, v216
	v_and_b32_e32 v235, 0xffff0000, v216
	v_sub_f32_e32 v215, v214, v207
	v_sub_f32_e32 v214, v218, v207
	v_sub_f32_e32 v217, v233, v207
	v_sub_f32_e32 v216, v219, v207
	v_sub_f32_e32 v219, v235, v207
	v_sub_f32_e32 v218, v234, v207
	v_sub_f32_e32 v235, v237, v207
	v_sub_f32_e32 v234, v236, v207
	v_pk_mul_f32 v[216:217], v[206:207], v[216:217] op_sel_hi:[0,1]
	v_pk_mul_f32 v[214:215], v[206:207], v[214:215] op_sel_hi:[0,1]
	v_pk_mul_f32 v[234:235], v[206:207], v[234:235] op_sel_hi:[0,1]
	v_pk_mul_f32 v[218:219], v[206:207], v[218:219] op_sel_hi:[0,1]
	v_pk_fma_f32 v[214:215], v[136:137], v[214:215], v[140:141]
	v_pk_fma_f32 v[216:217], v[138:139], v[216:217], v[142:143]
	v_pk_fma_f32 v[218:219], v[128:129], v[218:219], v[132:133]
	v_pk_fma_f32 v[234:235], v[130:131], v[234:235], v[134:135]
	v_pk_fma_f32 v[102:103], v[216:217], s[36:37], v[102:103] op_sel_hi:[1,0,1]
	v_pk_fma_f32 v[100:101], v[214:215], s[36:37], v[100:101] op_sel_hi:[1,0,1]
	v_pk_fma_f32 v[98:99], v[234:235], s[36:37], v[98:99] op_sel_hi:[1,0,1]
	v_pk_fma_f32 v[96:97], v[218:219], s[36:37], v[96:97] op_sel_hi:[1,0,1]
	v_cvt_pk_bf16_f32 v214, v100, v101
	v_cvt_pk_bf16_f32 v215, v102, v103
	v_cvt_pk_bf16_f32 v216, v96, v97
	v_cvt_pk_bf16_f32 v217, v98, v99
	global_store_dwordx4 v[198:199], v[214:217], off
	global_load_dwordx4 v[214:217], v[204:205], off
	v_mul_f32_e32 v218, 0x4f800000, v210
	v_cmp_gt_f32_e32 vcc, s78, v210
	s_waitcnt vmcnt(0)
	v_lshlrev_b32_e32 v236, 16, v217
	v_cndmask_b32_e32 v210, v210, v218, vcc
	v_sqrt_f32_e32 v218, v210
	v_and_b32_e32 v237, 0xffff0000, v217
	v_add_u32_e32 v219, -1, v218
	v_add_u32_e32 v233, 1, v218
	v_fma_f32 v234, -v219, v218, v210
	v_fma_f32 v235, -v233, v218, v210
	v_cmp_ge_f32_e64 s[0:1], 0, v234
	s_nop 1
	v_cndmask_b32_e64 v218, v218, v219, s[0:1]
	v_cmp_lt_f32_e64 s[0:1], 0, v235
	s_nop 1
	v_cndmask_b32_e64 v218, v218, v233, s[0:1]
	v_mul_f32_e32 v219, 0x37800000, v218
	v_cndmask_b32_e32 v218, v218, v219, vcc
	v_cmp_class_f32_e32 vcc, v210, v232
	s_nop 1
	v_cndmask_b32_e32 v210, v218, v210, vcc
	v_div_scale_f32 v218, s[0:1], v210, v210, 1.0
	v_rcp_f32_e32 v219, v218
	v_div_scale_f32 v233, vcc, 1.0, v210, 1.0
	v_fma_f32 v234, -v218, v219, 1.0
	v_fmac_f32_e32 v219, v234, v219
	v_mul_f32_e32 v234, v233, v219
	v_fma_f32 v235, -v218, v234, v233
	v_fmac_f32_e32 v234, v235, v219
	v_fma_f32 v218, -v218, v234, v233
	v_div_fmas_f32 v218, v218, v219, v234
	v_div_fixup_f32 v210, v218, v210, 1.0
	v_lshlrev_b32_e32 v218, 16, v214
	v_and_b32_e32 v214, 0xffff0000, v214
	v_lshlrev_b32_e32 v219, 16, v215
	v_and_b32_e32 v233, 0xffff0000, v215
	v_lshlrev_b32_e32 v234, 16, v216
	v_and_b32_e32 v235, 0xffff0000, v216
	v_sub_f32_e32 v215, v214, v211
	v_sub_f32_e32 v214, v218, v211
	v_sub_f32_e32 v217, v233, v211
	v_sub_f32_e32 v216, v219, v211
	v_sub_f32_e32 v219, v235, v211
	v_sub_f32_e32 v218, v234, v211
	v_sub_f32_e32 v235, v237, v211
	v_sub_f32_e32 v234, v236, v211
	v_pk_mul_f32 v[216:217], v[210:211], v[216:217] op_sel_hi:[0,1]
	v_pk_mul_f32 v[214:215], v[210:211], v[214:215] op_sel_hi:[0,1]
	v_pk_mul_f32 v[234:235], v[210:211], v[234:235] op_sel_hi:[0,1]
	v_pk_mul_f32 v[218:219], v[210:211], v[218:219] op_sel_hi:[0,1]
	v_pk_fma_f32 v[214:215], v[136:137], v[214:215], v[140:141]
	v_pk_fma_f32 v[216:217], v[138:139], v[216:217], v[142:143]
	v_pk_fma_f32 v[218:219], v[128:129], v[218:219], v[132:133]
	v_pk_fma_f32 v[234:235], v[130:131], v[234:235], v[134:135]
	v_pk_fma_f32 v[94:95], v[216:217], s[36:37], v[94:95] op_sel_hi:[1,0,1]
	v_pk_fma_f32 v[92:93], v[214:215], s[36:37], v[92:93] op_sel_hi:[1,0,1]
	v_pk_fma_f32 v[90:91], v[234:235], s[36:37], v[90:91] op_sel_hi:[1,0,1]
	v_pk_fma_f32 v[88:89], v[218:219], s[36:37], v[88:89] op_sel_hi:[1,0,1]
	v_cvt_pk_bf16_f32 v214, v92, v93
	v_cvt_pk_bf16_f32 v215, v94, v95
	v_cvt_pk_bf16_f32 v216, v88, v89
	v_cvt_pk_bf16_f32 v217, v90, v91
	global_store_dwordx4 v[204:205], v[214:217], off
	global_load_dwordx4 v[234:237], v[208:209], off
	s_waitcnt vmcnt(0)
	v_and_b32_e32 v219, 0xffff0000, v236
	v_pk_mul_f32 v[216:217], v[212:213], s[34:35] op_sel:[1,0] op_sel_hi:[0,0]
	v_fma_f32 v212, -v217, v217, v216
	v_max_f32_e32 v212, 0, v212
	v_add_f32_e32 v212, 0x3727c5ac, v212
	v_mul_f32_e32 v213, 0x4f800000, v212
	v_cmp_gt_f32_e32 vcc, s78, v212
	v_lshlrev_b32_e32 v233, 16, v237
	v_sub_f32_e32 v219, v219, v217
	v_cndmask_b32_e32 v212, v212, v213, vcc
	v_sqrt_f32_e32 v213, v212
	s_nop 0
	v_add_u32_e32 v214, -1, v213
	v_add_u32_e32 v215, 1, v213
	v_fma_f32 v216, -v214, v213, v212
	v_fma_f32 v218, -v215, v213, v212
	v_cmp_ge_f32_e64 s[0:1], 0, v216
	s_nop 1
	v_cndmask_b32_e64 v213, v213, v214, s[0:1]
	v_cmp_lt_f32_e64 s[0:1], 0, v218
	s_nop 1
	v_cndmask_b32_e64 v213, v213, v215, s[0:1]
	v_mul_f32_e32 v214, 0x37800000, v213
	v_cndmask_b32_e32 v213, v213, v214, vcc
	v_cmp_class_f32_e32 vcc, v212, v232
	v_lshl_add_u64 v[214:215], v[184:185], 0, v[178:179]
	s_nop 0
	v_cndmask_b32_e32 v212, v213, v212, vcc
	v_div_scale_f32 v213, s[0:1], v212, v212, 1.0
	v_rcp_f32_e32 v216, v213
	v_div_scale_f32 v184, vcc, 1.0, v212, 1.0
	v_fma_f32 v185, -v213, v216, 1.0
	v_fmac_f32_e32 v216, v185, v216
	v_mul_f32_e32 v185, v184, v216
	v_fma_f32 v218, -v213, v185, v184
	v_fmac_f32_e32 v185, v218, v216
	v_fma_f32 v184, -v213, v185, v184
	v_div_fmas_f32 v184, v184, v216, v185
	v_div_fixup_f32 v216, v184, v212, 1.0
	v_lshlrev_b32_e32 v184, 16, v234
	v_and_b32_e32 v185, 0xffff0000, v234
	v_lshlrev_b32_e32 v212, 16, v235
	v_and_b32_e32 v213, 0xffff0000, v235
	v_lshlrev_b32_e32 v218, 16, v236
	v_and_b32_e32 v234, 0xffff0000, v237
	v_sub_f32_e32 v185, v185, v217
	v_sub_f32_e32 v184, v184, v217
	v_sub_f32_e32 v213, v213, v217
	v_sub_f32_e32 v212, v212, v217
	v_sub_f32_e32 v218, v218, v217
	v_sub_f32_e32 v235, v234, v217
	v_sub_f32_e32 v234, v233, v217
	v_pk_mul_f32 v[212:213], v[216:217], v[212:213] op_sel_hi:[0,1]
	v_pk_mul_f32 v[184:185], v[216:217], v[184:185] op_sel_hi:[0,1]
	v_pk_mul_f32 v[234:235], v[216:217], v[234:235] op_sel_hi:[0,1]
	v_pk_mul_f32 v[218:219], v[216:217], v[218:219] op_sel_hi:[0,1]
	v_pk_fma_f32 v[184:185], v[136:137], v[184:185], v[140:141]
	v_pk_fma_f32 v[212:213], v[138:139], v[212:213], v[142:143]
	v_pk_fma_f32 v[218:219], v[128:129], v[218:219], v[132:133]
	v_pk_fma_f32 v[234:235], v[130:131], v[234:235], v[134:135]
	v_pk_fma_f32 v[86:87], v[212:213], s[36:37], v[86:87] op_sel_hi:[1,0,1]
	v_pk_fma_f32 v[84:85], v[184:185], s[36:37], v[84:85] op_sel_hi:[1,0,1]
	v_pk_fma_f32 v[82:83], v[234:235], s[36:37], v[82:83] op_sel_hi:[1,0,1]
	v_pk_fma_f32 v[80:81], v[218:219], s[36:37], v[80:81] op_sel_hi:[1,0,1]
	v_cvt_pk_bf16_f32 v234, v84, v85
	v_cvt_pk_bf16_f32 v235, v86, v87
	v_cvt_pk_bf16_f32 v236, v80, v81
	v_cvt_pk_bf16_f32 v237, v82, v83
	global_store_dwordx4 v[208:209], v[234:237], off
	global_load_dwordx4 v[234:237], v[214:215], off
	v_pk_mul_f32 v[218:219], v[182:183], s[34:35] op_sel:[1,0] op_sel_hi:[0,0]
	v_fma_f32 v182, -v219, v219, v218
	v_max_f32_e32 v182, 0, v182
	v_add_f32_e32 v182, 0x3727c5ac, v182
	v_mul_f32_e32 v183, 0x4f800000, v182
	v_cmp_gt_f32_e32 vcc, s78, v182
	s_nop 1
	v_cndmask_b32_e32 v182, v182, v183, vcc
	v_sqrt_f32_e32 v183, v182
	s_nop 0
	v_add_u32_e32 v184, -1, v183
	v_add_u32_e32 v185, 1, v183
	v_fma_f32 v212, -v184, v183, v182
	v_fma_f32 v213, -v185, v183, v182
	v_cmp_ge_f32_e64 s[0:1], 0, v212
	s_nop 1
	v_cndmask_b32_e64 v183, v183, v184, s[0:1]
	v_cmp_lt_f32_e64 s[0:1], 0, v213
	v_lshl_add_u64 v[212:213], v[180:181], 0, v[178:179]
	s_waitcnt vmcnt(0)
	v_and_b32_e32 v181, 0xffff0000, v235
	v_cndmask_b32_e64 v183, v183, v185, s[0:1]
	v_mul_f32_e32 v184, 0x37800000, v183
	v_cndmask_b32_e32 v183, v183, v184, vcc
	v_cmp_class_f32_e32 vcc, v182, v232
	v_and_b32_e32 v185, 0xffff0000, v237
	v_sub_f32_e32 v181, v181, v219
	v_cndmask_b32_e32 v182, v183, v182, vcc
	v_div_scale_f32 v183, s[0:1], v182, v182, 1.0
	v_rcp_f32_e32 v184, v183
	v_div_scale_f32 v178, vcc, 1.0, v182, 1.0
	v_sub_f32_e32 v185, v185, v219
	v_fma_f32 v179, -v183, v184, 1.0
	v_fmac_f32_e32 v184, v179, v184
	v_mul_f32_e32 v179, v178, v184
	v_fma_f32 v180, -v183, v179, v178
	v_fmac_f32_e32 v179, v180, v184
	v_fma_f32 v178, -v183, v179, v178
	v_div_fmas_f32 v178, v178, v184, v179
	v_div_fixup_f32 v218, v178, v182, 1.0
	v_lshlrev_b32_e32 v178, 16, v234
	v_and_b32_e32 v179, 0xffff0000, v234
	v_lshlrev_b32_e32 v180, 16, v235
	v_lshlrev_b32_e32 v182, 16, v236
	v_and_b32_e32 v183, 0xffff0000, v236
	v_lshlrev_b32_e32 v184, 16, v237
	v_sub_f32_e32 v179, v179, v219
	v_sub_f32_e32 v178, v178, v219
	v_sub_f32_e32 v180, v180, v219
	v_sub_f32_e32 v183, v183, v219
	v_sub_f32_e32 v182, v182, v219
	v_sub_f32_e32 v184, v184, v219
	v_pk_mul_f32 v[180:181], v[218:219], v[180:181] op_sel_hi:[0,1]
	v_pk_mul_f32 v[178:179], v[218:219], v[178:179] op_sel_hi:[0,1]
	v_pk_mul_f32 v[184:185], v[218:219], v[184:185] op_sel_hi:[0,1]
	v_pk_mul_f32 v[182:183], v[218:219], v[182:183] op_sel_hi:[0,1]
	v_pk_fma_f32 v[178:179], v[136:137], v[178:179], v[140:141]
	v_pk_fma_f32 v[180:181], v[138:139], v[180:181], v[142:143]
	v_pk_fma_f32 v[234:235], v[128:129], v[182:183], v[132:133]
	v_pk_fma_f32 v[236:237], v[130:131], v[184:185], v[134:135]
	v_pk_fma_f32 v[182:183], v[180:181], s[36:37], v[78:79] op_sel_hi:[1,0,1]
	v_pk_fma_f32 v[184:185], v[178:179], s[36:37], v[76:77] op_sel_hi:[1,0,1]
	v_pk_fma_f32 v[178:179], v[236:237], s[36:37], v[74:75] op_sel_hi:[1,0,1]
	v_pk_fma_f32 v[180:181], v[234:235], s[36:37], v[72:73] op_sel_hi:[1,0,1]
	v_cvt_pk_bf16_f32 v72, v184, v185
	v_cvt_pk_bf16_f32 v73, v182, v183
	v_cvt_pk_bf16_f32 v74, v180, v181
	v_cvt_pk_bf16_f32 v75, v178, v179
	global_store_dwordx4 v[214:215], v[72:75], off
	global_load_dwordx4 v[72:75], v[212:213], off
	v_fma_f32 v76, -v203, v203, v202
	v_max_f32_e32 v76, 0, v76
	v_add_f32_e32 v76, 0x3727c5ac, v76
	v_mul_f32_e32 v77, 0x4f800000, v76
	v_cmp_gt_f32_e32 vcc, s78, v76
	s_waitcnt vmcnt(0)
	v_lshlrev_b32_e32 v234, 16, v75
	v_cndmask_b32_e32 v76, v76, v77, vcc
	v_sqrt_f32_e32 v77, v76
	v_and_b32_e32 v235, 0xffff0000, v75
	v_add_u32_e32 v78, -1, v77
	v_add_u32_e32 v79, 1, v77
	v_fma_f32 v202, -v78, v77, v76
	v_fma_f32 v233, -v79, v77, v76
	v_cmp_ge_f32_e64 s[0:1], 0, v202
	s_nop 1
	v_cndmask_b32_e64 v77, v77, v78, s[0:1]
	v_cmp_lt_f32_e64 s[0:1], 0, v233
	s_nop 1
	v_cndmask_b32_e64 v77, v77, v79, s[0:1]
	v_mul_f32_e32 v78, 0x37800000, v77
	v_cndmask_b32_e32 v77, v77, v78, vcc
	v_cmp_class_f32_e32 vcc, v76, v232
	s_nop 1
	v_cndmask_b32_e32 v76, v77, v76, vcc
	v_div_scale_f32 v77, s[0:1], v76, v76, 1.0
	v_rcp_f32_e32 v78, v77
	v_div_scale_f32 v79, vcc, 1.0, v76, 1.0
	v_fma_f32 v202, -v77, v78, 1.0
	v_fmac_f32_e32 v78, v202, v78
	v_mul_f32_e32 v202, v79, v78
	v_fma_f32 v233, -v77, v202, v79
	v_fmac_f32_e32 v202, v233, v78
	v_fma_f32 v77, -v77, v202, v79
	v_div_fmas_f32 v77, v77, v78, v202
	v_div_fixup_f32 v202, v77, v76, 1.0
	v_lshlrev_b32_e32 v76, 16, v72
	v_and_b32_e32 v72, 0xffff0000, v72
	v_lshlrev_b32_e32 v77, 16, v73
	v_and_b32_e32 v78, 0xffff0000, v73
	v_lshlrev_b32_e32 v79, 16, v74
	v_and_b32_e32 v233, 0xffff0000, v74
	v_sub_f32_e32 v73, v72, v203
	v_sub_f32_e32 v72, v76, v203
	v_sub_f32_e32 v75, v78, v203
	v_sub_f32_e32 v74, v77, v203
	v_sub_f32_e32 v77, v233, v203
	v_sub_f32_e32 v76, v79, v203
	v_sub_f32_e32 v79, v235, v203
	v_sub_f32_e32 v78, v234, v203
	v_pk_mul_f32 v[74:75], v[202:203], v[74:75] op_sel_hi:[0,1]
	v_pk_mul_f32 v[72:73], v[202:203], v[72:73] op_sel_hi:[0,1]
	v_pk_mul_f32 v[78:79], v[202:203], v[78:79] op_sel_hi:[0,1]
	v_pk_mul_f32 v[76:77], v[202:203], v[76:77] op_sel_hi:[0,1]
	v_pk_fma_f32 v[72:73], v[136:137], v[72:73], v[140:141]
	v_pk_fma_f32 v[74:75], v[138:139], v[74:75], v[142:143]
	v_pk_fma_f32 v[76:77], v[128:129], v[76:77], v[132:133]
	v_pk_fma_f32 v[78:79], v[130:131], v[78:79], v[134:135]
	v_pk_fma_f32 v[130:131], v[74:75], s[36:37], v[70:71] op_sel_hi:[1,0,1]
	v_pk_fma_f32 v[134:135], v[72:73], s[36:37], v[68:69] op_sel_hi:[1,0,1]
	v_pk_fma_f32 v[128:129], v[78:79], s[36:37], v[66:67] op_sel_hi:[1,0,1]
	v_pk_fma_f32 v[132:133], v[76:77], s[36:37], v[64:65] op_sel_hi:[1,0,1]
	v_cvt_pk_bf16_f32 v64, v134, v135
	v_cvt_pk_bf16_f32 v65, v130, v131
	v_cvt_pk_bf16_f32 v66, v132, v133
	v_cvt_pk_bf16_f32 v67, v128, v129
	global_store_dwordx4 v[212:213], v[64:67], off
	global_load_dwordx4 v[136:139], v[176:177], off offset:256
	global_load_dwordx4 v[68:71], v[190:191], off offset:512
	global_load_dwordx4 v[72:75], v[188:189], off offset:512
	global_load_dwordx4 v[64:67], v[188:189], off offset:528
	global_load_dwordx4 v[76:79], v[190:191], off offset:528
	s_waitcnt vmcnt(0)
	v_lshlrev_b32_e32 v140, 16, v136
	v_and_b32_e32 v136, 0xffff0000, v136
	v_lshlrev_b32_e32 v141, 16, v137
	v_and_b32_e32 v142, 0xffff0000, v137
	v_lshlrev_b32_e32 v143, 16, v138
	v_and_b32_e32 v188, 0xffff0000, v138
	v_lshlrev_b32_e32 v189, 16, v139
	v_and_b32_e32 v190, 0xffff0000, v139
	v_sub_f32_e32 v137, v136, v187
	v_sub_f32_e32 v136, v140, v187
	v_sub_f32_e32 v139, v142, v187
	v_sub_f32_e32 v138, v141, v187
	v_sub_f32_e32 v141, v188, v187
	v_sub_f32_e32 v140, v143, v187
	v_sub_f32_e32 v143, v190, v187
	v_sub_f32_e32 v142, v189, v187
	v_pk_mul_f32 v[138:139], v[186:187], v[138:139] op_sel_hi:[0,1]
	v_pk_mul_f32 v[136:137], v[186:187], v[136:137] op_sel_hi:[0,1]
	v_pk_mul_f32 v[142:143], v[186:187], v[142:143] op_sel_hi:[0,1]
	v_pk_mul_f32 v[140:141], v[186:187], v[140:141] op_sel_hi:[0,1]
	v_pk_fma_f32 v[136:137], v[72:73], v[136:137], v[68:69]
	v_pk_fma_f32 v[138:139], v[74:75], v[138:139], v[70:71]
	v_pk_fma_f32 v[140:141], v[64:65], v[140:141], v[76:77]
	v_pk_fma_f32 v[142:143], v[66:67], v[142:143], v[78:79]
	v_pk_fma_f32 v[62:63], v[138:139], s[36:37], v[62:63] op_sel_hi:[1,0,1]
	v_pk_fma_f32 v[60:61], v[136:137], s[36:37], v[60:61] op_sel_hi:[1,0,1]
	v_pk_fma_f32 v[58:59], v[142:143], s[36:37], v[58:59] op_sel_hi:[1,0,1]
	v_pk_fma_f32 v[56:57], v[140:141], s[36:37], v[56:57] op_sel_hi:[1,0,1]
	v_cvt_pk_bf16_f32 v136, v60, v61
	v_cvt_pk_bf16_f32 v137, v62, v63
	v_cvt_pk_bf16_f32 v138, v56, v57
	v_cvt_pk_bf16_f32 v139, v58, v59
	global_store_dwordx4 v[176:177], v[136:139], off offset:256
	global_load_dwordx4 v[244:247], v[192:193], off offset:256
	global_load_dwordx4 v[240:243], v[194:195], off offset:256
	s_nop 0
	s_waitcnt vmcnt(1)
	v_lshlrev_b32_e32 v140, 16, v244
	v_and_b32_e32 v136, 0xffff0000, v244
	v_lshlrev_b32_e32 v141, 16, v245
	v_and_b32_e32 v142, 0xffff0000, v245
	v_lshlrev_b32_e32 v143, 16, v246
	v_and_b32_e32 v176, 0xffff0000, v246
	v_lshlrev_b32_e32 v177, 16, v247
	v_and_b32_e32 v186, 0xffff0000, v247
	v_sub_f32_e32 v137, v136, v197
	v_sub_f32_e32 v136, v140, v197
	v_sub_f32_e32 v139, v142, v197
	v_sub_f32_e32 v138, v141, v197
	v_sub_f32_e32 v141, v176, v197
	v_sub_f32_e32 v140, v143, v197
	v_sub_f32_e32 v143, v186, v197
	v_sub_f32_e32 v142, v177, v197
	v_pk_mul_f32 v[138:139], v[196:197], v[138:139] op_sel_hi:[0,1]
	v_pk_mul_f32 v[136:137], v[196:197], v[136:137] op_sel_hi:[0,1]
	v_pk_mul_f32 v[142:143], v[196:197], v[142:143] op_sel_hi:[0,1]
	v_pk_mul_f32 v[140:141], v[196:197], v[140:141] op_sel_hi:[0,1]
	v_pk_fma_f32 v[136:137], v[72:73], v[136:137], v[68:69]
	v_pk_fma_f32 v[138:139], v[74:75], v[138:139], v[70:71]
	v_pk_fma_f32 v[140:141], v[64:65], v[140:141], v[76:77]
	v_pk_fma_f32 v[142:143], v[66:67], v[142:143], v[78:79]
	v_pk_fma_f32 v[54:55], v[138:139], s[36:37], v[54:55] op_sel_hi:[1,0,1]
	v_pk_fma_f32 v[52:53], v[136:137], s[36:37], v[52:53] op_sel_hi:[1,0,1]
	v_pk_fma_f32 v[50:51], v[142:143], s[36:37], v[50:51] op_sel_hi:[1,0,1]
	v_pk_fma_f32 v[48:49], v[140:141], s[36:37], v[48:49] op_sel_hi:[1,0,1]
	v_cvt_pk_bf16_f32 v136, v52, v53
	v_cvt_pk_bf16_f32 v137, v54, v55
	v_cvt_pk_bf16_f32 v138, v48, v49
	v_cvt_pk_bf16_f32 v139, v50, v51
	global_store_dwordx4 v[192:193], v[136:139], off offset:256
	global_load_dwordx4 v[244:247], v[198:199], off offset:256
	s_nop 0
	s_waitcnt vmcnt(2)
	v_lshlrev_b32_e32 v140, 16, v240
	v_and_b32_e32 v136, 0xffff0000, v240
	v_lshlrev_b32_e32 v141, 16, v241
	v_and_b32_e32 v142, 0xffff0000, v241
	v_lshlrev_b32_e32 v143, 16, v242
	v_and_b32_e32 v176, 0xffff0000, v242
	v_lshlrev_b32_e32 v177, 16, v243
	v_and_b32_e32 v186, 0xffff0000, v243
	v_sub_f32_e32 v137, v136, v201
	v_sub_f32_e32 v136, v140, v201
	v_sub_f32_e32 v139, v142, v201
	v_sub_f32_e32 v138, v141, v201
	v_sub_f32_e32 v141, v176, v201
	v_sub_f32_e32 v140, v143, v201
	v_sub_f32_e32 v143, v186, v201
	v_sub_f32_e32 v142, v177, v201
	v_pk_mul_f32 v[138:139], v[200:201], v[138:139] op_sel_hi:[0,1]
	v_pk_mul_f32 v[136:137], v[200:201], v[136:137] op_sel_hi:[0,1]
	v_pk_mul_f32 v[142:143], v[200:201], v[142:143] op_sel_hi:[0,1]
	v_pk_mul_f32 v[140:141], v[200:201], v[140:141] op_sel_hi:[0,1]
	v_pk_fma_f32 v[136:137], v[72:73], v[136:137], v[68:69]
	v_pk_fma_f32 v[138:139], v[74:75], v[138:139], v[70:71]
	v_pk_fma_f32 v[140:141], v[64:65], v[140:141], v[76:77]
	v_pk_fma_f32 v[142:143], v[66:67], v[142:143], v[78:79]
	v_pk_fma_f32 v[46:47], v[138:139], s[36:37], v[46:47] op_sel_hi:[1,0,1]
	v_pk_fma_f32 v[44:45], v[136:137], s[36:37], v[44:45] op_sel_hi:[1,0,1]
	v_pk_fma_f32 v[42:43], v[142:143], s[36:37], v[42:43] op_sel_hi:[1,0,1]
	v_pk_fma_f32 v[40:41], v[140:141], s[36:37], v[40:41] op_sel_hi:[1,0,1]
	v_cvt_pk_bf16_f32 v136, v44, v45
	v_cvt_pk_bf16_f32 v137, v46, v47
	v_cvt_pk_bf16_f32 v138, v40, v41
	v_cvt_pk_bf16_f32 v139, v42, v43
	global_store_dwordx4 v[194:195], v[136:139], off offset:256
	global_load_dwordx4 v[240:243], v[204:205], off offset:256
	s_nop 0
	s_waitcnt vmcnt(2)
	v_lshlrev_b32_e32 v140, 16, v244
	v_and_b32_e32 v136, 0xffff0000, v244
	v_lshlrev_b32_e32 v141, 16, v245
	v_and_b32_e32 v142, 0xffff0000, v245
	v_lshlrev_b32_e32 v143, 16, v246
	v_and_b32_e32 v176, 0xffff0000, v246
	v_lshlrev_b32_e32 v177, 16, v247
	v_and_b32_e32 v186, 0xffff0000, v247
	v_sub_f32_e32 v137, v136, v207
	v_sub_f32_e32 v136, v140, v207
	v_sub_f32_e32 v139, v142, v207
	v_sub_f32_e32 v138, v141, v207
	v_sub_f32_e32 v141, v176, v207
	v_sub_f32_e32 v140, v143, v207
	v_sub_f32_e32 v143, v186, v207
	v_sub_f32_e32 v142, v177, v207
	v_pk_mul_f32 v[138:139], v[206:207], v[138:139] op_sel_hi:[0,1]
	v_pk_mul_f32 v[136:137], v[206:207], v[136:137] op_sel_hi:[0,1]
	v_pk_mul_f32 v[142:143], v[206:207], v[142:143] op_sel_hi:[0,1]
	v_pk_mul_f32 v[140:141], v[206:207], v[140:141] op_sel_hi:[0,1]
	v_pk_fma_f32 v[136:137], v[72:73], v[136:137], v[68:69]
	v_pk_fma_f32 v[138:139], v[74:75], v[138:139], v[70:71]
	v_pk_fma_f32 v[140:141], v[64:65], v[140:141], v[76:77]
	v_pk_fma_f32 v[142:143], v[66:67], v[142:143], v[78:79]
	v_pk_fma_f32 v[38:39], v[138:139], s[36:37], v[38:39] op_sel_hi:[1,0,1]
	v_pk_fma_f32 v[36:37], v[136:137], s[36:37], v[36:37] op_sel_hi:[1,0,1]
	v_pk_fma_f32 v[34:35], v[142:143], s[36:37], v[34:35] op_sel_hi:[1,0,1]
	v_pk_fma_f32 v[32:33], v[140:141], s[36:37], v[32:33] op_sel_hi:[1,0,1]
	v_cvt_pk_bf16_f32 v136, v36, v37
	v_cvt_pk_bf16_f32 v137, v38, v39
	v_cvt_pk_bf16_f32 v138, v32, v33
	v_cvt_pk_bf16_f32 v139, v34, v35
	global_store_dwordx4 v[198:199], v[136:139], off offset:256
	global_load_dwordx4 v[244:247], v[208:209], off offset:256
	s_nop 0
	s_waitcnt vmcnt(2)
	v_lshlrev_b32_e32 v140, 16, v240
	v_and_b32_e32 v136, 0xffff0000, v240
	v_lshlrev_b32_e32 v141, 16, v241
	v_and_b32_e32 v142, 0xffff0000, v241
	v_lshlrev_b32_e32 v143, 16, v242
	v_and_b32_e32 v176, 0xffff0000, v242
	v_lshlrev_b32_e32 v177, 16, v243
	v_and_b32_e32 v186, 0xffff0000, v243
	v_sub_f32_e32 v137, v136, v211
	v_sub_f32_e32 v136, v140, v211
	v_sub_f32_e32 v139, v142, v211
	v_sub_f32_e32 v138, v141, v211
	v_sub_f32_e32 v141, v176, v211
	v_sub_f32_e32 v140, v143, v211
	v_sub_f32_e32 v143, v186, v211
	v_sub_f32_e32 v142, v177, v211
	v_pk_mul_f32 v[138:139], v[210:211], v[138:139] op_sel_hi:[0,1]
	v_pk_mul_f32 v[136:137], v[210:211], v[136:137] op_sel_hi:[0,1]
	v_pk_mul_f32 v[142:143], v[210:211], v[142:143] op_sel_hi:[0,1]
	v_pk_mul_f32 v[140:141], v[210:211], v[140:141] op_sel_hi:[0,1]
	v_pk_fma_f32 v[136:137], v[72:73], v[136:137], v[68:69]
	v_pk_fma_f32 v[138:139], v[74:75], v[138:139], v[70:71]
	v_pk_fma_f32 v[140:141], v[64:65], v[140:141], v[76:77]
	v_pk_fma_f32 v[142:143], v[66:67], v[142:143], v[78:79]
	v_pk_fma_f32 v[30:31], v[138:139], s[36:37], v[30:31] op_sel_hi:[1,0,1]
	v_pk_fma_f32 v[28:29], v[136:137], s[36:37], v[28:29] op_sel_hi:[1,0,1]
	v_pk_fma_f32 v[26:27], v[142:143], s[36:37], v[26:27] op_sel_hi:[1,0,1]
	v_pk_fma_f32 v[24:25], v[140:141], s[36:37], v[24:25] op_sel_hi:[1,0,1]
	v_cvt_pk_bf16_f32 v136, v28, v29
	v_cvt_pk_bf16_f32 v137, v30, v31
	v_cvt_pk_bf16_f32 v138, v24, v25
	v_cvt_pk_bf16_f32 v139, v26, v27
	global_store_dwordx4 v[204:205], v[136:139], off offset:256
	global_load_dwordx4 v[240:243], v[214:215], off offset:256
	s_nop 0
	s_waitcnt vmcnt(2)
	v_lshlrev_b32_e32 v140, 16, v244
	v_and_b32_e32 v136, 0xffff0000, v244
	v_lshlrev_b32_e32 v141, 16, v245
	v_and_b32_e32 v142, 0xffff0000, v245
	v_lshlrev_b32_e32 v143, 16, v246
	v_and_b32_e32 v176, 0xffff0000, v246
	v_lshlrev_b32_e32 v177, 16, v247
	v_and_b32_e32 v186, 0xffff0000, v247
	v_sub_f32_e32 v137, v136, v217
	v_sub_f32_e32 v136, v140, v217
	v_sub_f32_e32 v139, v142, v217
	v_sub_f32_e32 v138, v141, v217
	v_sub_f32_e32 v141, v176, v217
	v_sub_f32_e32 v140, v143, v217
	v_sub_f32_e32 v143, v186, v217
	v_sub_f32_e32 v142, v177, v217
	v_pk_mul_f32 v[138:139], v[216:217], v[138:139] op_sel_hi:[0,1]
	v_pk_mul_f32 v[136:137], v[216:217], v[136:137] op_sel_hi:[0,1]
	v_pk_mul_f32 v[142:143], v[216:217], v[142:143] op_sel_hi:[0,1]
	v_pk_mul_f32 v[140:141], v[216:217], v[140:141] op_sel_hi:[0,1]
	v_pk_fma_f32 v[136:137], v[72:73], v[136:137], v[68:69]
	v_pk_fma_f32 v[138:139], v[74:75], v[138:139], v[70:71]
	v_pk_fma_f32 v[140:141], v[64:65], v[140:141], v[76:77]
	v_pk_fma_f32 v[142:143], v[66:67], v[142:143], v[78:79]
	v_pk_fma_f32 v[22:23], v[138:139], s[36:37], v[22:23] op_sel_hi:[1,0,1]
	v_pk_fma_f32 v[20:21], v[136:137], s[36:37], v[20:21] op_sel_hi:[1,0,1]
	v_pk_fma_f32 v[18:19], v[142:143], s[36:37], v[18:19] op_sel_hi:[1,0,1]
	v_pk_fma_f32 v[16:17], v[140:141], s[36:37], v[16:17] op_sel_hi:[1,0,1]
	v_cvt_pk_bf16_f32 v136, v20, v21
	v_cvt_pk_bf16_f32 v137, v22, v23
	v_cvt_pk_bf16_f32 v138, v16, v17
	v_cvt_pk_bf16_f32 v139, v18, v19
	global_store_dwordx4 v[208:209], v[136:139], off offset:256
	s_nop 0
	s_waitcnt vmcnt(1)
	v_lshlrev_b32_e32 v140, 16, v240
	v_and_b32_e32 v136, 0xffff0000, v240
	v_lshlrev_b32_e32 v141, 16, v241
	v_and_b32_e32 v142, 0xffff0000, v241
	v_lshlrev_b32_e32 v143, 16, v242
	v_and_b32_e32 v176, 0xffff0000, v242
	v_lshlrev_b32_e32 v177, 16, v243
	v_and_b32_e32 v186, 0xffff0000, v243
	v_sub_f32_e32 v137, v136, v219
	v_sub_f32_e32 v136, v140, v219
	v_sub_f32_e32 v139, v142, v219
	v_sub_f32_e32 v138, v141, v219
	v_sub_f32_e32 v141, v176, v219
	v_sub_f32_e32 v140, v143, v219
	v_sub_f32_e32 v143, v186, v219
	v_sub_f32_e32 v142, v177, v219
	v_pk_mul_f32 v[138:139], v[218:219], v[138:139] op_sel_hi:[0,1]
	v_pk_mul_f32 v[136:137], v[218:219], v[136:137] op_sel_hi:[0,1]
	v_pk_mul_f32 v[142:143], v[218:219], v[142:143] op_sel_hi:[0,1]
	v_pk_mul_f32 v[140:141], v[218:219], v[140:141] op_sel_hi:[0,1]
	v_pk_fma_f32 v[136:137], v[72:73], v[136:137], v[68:69]
	v_pk_fma_f32 v[138:139], v[74:75], v[138:139], v[70:71]
	v_pk_fma_f32 v[140:141], v[64:65], v[140:141], v[76:77]
	v_pk_fma_f32 v[142:143], v[66:67], v[142:143], v[78:79]
	v_pk_fma_f32 v[14:15], v[138:139], s[36:37], v[14:15] op_sel_hi:[1,0,1]
	v_pk_fma_f32 v[12:13], v[136:137], s[36:37], v[12:13] op_sel_hi:[1,0,1]
	v_pk_fma_f32 v[10:11], v[142:143], s[36:37], v[10:11] op_sel_hi:[1,0,1]
	v_pk_fma_f32 v[8:9], v[140:141], s[36:37], v[8:9] op_sel_hi:[1,0,1]
	v_cvt_pk_bf16_f32 v136, v12, v13
	v_cvt_pk_bf16_f32 v137, v14, v15
	v_cvt_pk_bf16_f32 v138, v8, v9
	v_cvt_pk_bf16_f32 v139, v10, v11
	global_store_dwordx4 v[214:215], v[136:139], off offset:256
	global_load_dwordx4 v[136:139], v[212:213], off offset:256
	v_add_f32_e32 v140, v124, v125
	v_add_f32_e32 v141, v126, v127
	v_add_f32_e32 v142, v120, v121
	v_add_f32_e32 v143, v122, v123
	v_mul_f32_e32 v125, v125, v125
	v_mul_f32_e32 v127, v127, v127
	v_mul_f32_e32 v121, v121, v121
	v_mul_f32_e32 v123, v123, v123
	v_fmac_f32_e32 v125, v124, v124
	v_fmac_f32_e32 v127, v126, v126
	v_fmac_f32_e32 v121, v120, v120
	v_fmac_f32_e32 v123, v122, v122
	v_add_f32_e32 v122, v125, v127
	v_add_f32_e32 v121, v121, v123
	v_add_f32_e32 v121, v122, v121
	v_add_f32_e32 v122, v60, v61
	v_add_f32_e32 v123, v62, v63
	v_add_f32_e32 v124, v56, v57
	v_add_f32_e32 v125, v58, v59
	v_mul_f32_e32 v61, v61, v61
	v_mul_f32_e32 v63, v63, v63
	v_mul_f32_e32 v57, v57, v57
	v_mul_f32_e32 v59, v59, v59
	v_add_f32_e32 v140, v140, v141
	v_add_f32_e32 v141, v142, v143
	v_fmac_f32_e32 v61, v60, v60
	v_fmac_f32_e32 v63, v62, v62
	v_fmac_f32_e32 v57, v56, v56
	v_fmac_f32_e32 v59, v58, v58
	v_add_f32_e32 v120, v140, v141
	v_add_f32_e32 v122, v122, v123
	v_add_f32_e32 v123, v124, v125
	v_add_f32_e32 v58, v61, v63
	v_add_f32_e32 v57, v57, v59
	v_add_f32_e32 v120, 0, v120
	v_add_f32_e32 v56, v122, v123
	v_add_f32_e32 v57, v58, v57
	v_add_f32_e32 v56, v120, v56
	v_add_f32_e32 v59, v121, v57
	ds_bpermute_b32 v58, v226, v56
	ds_bpermute_b32 v60, v226, v59
	s_waitcnt lgkmcnt(0)
	v_add_f32_e32 v56, v56, v58
	v_add_f32_e32 v58, v59, v60
	ds_bpermute_b32 v57, v227, v56
	s_waitcnt vmcnt(0)
	v_lshlrev_b32_e32 v59, 16, v136
	v_and_b32_e32 v60, 0xffff0000, v136
	v_lshlrev_b32_e32 v62, 16, v137
	v_and_b32_e32 v63, 0xffff0000, v137
	v_lshlrev_b32_e32 v120, 16, v138
	v_and_b32_e32 v121, 0xffff0000, v138
	v_lshlrev_b32_e32 v122, 16, v139
	v_and_b32_e32 v123, 0xffff0000, v139
	v_sub_f32_e32 v61, v60, v203
	v_sub_f32_e32 v60, v59, v203
	v_sub_f32_e32 v63, v63, v203
	v_sub_f32_e32 v62, v62, v203
	v_sub_f32_e32 v121, v121, v203
	v_sub_f32_e32 v120, v120, v203
	v_sub_f32_e32 v123, v123, v203
	v_sub_f32_e32 v122, v122, v203
	v_pk_mul_f32 v[62:63], v[202:203], v[62:63] op_sel_hi:[0,1]
	v_pk_mul_f32 v[60:61], v[202:203], v[60:61] op_sel_hi:[0,1]
	v_pk_mul_f32 v[122:123], v[202:203], v[122:123] op_sel_hi:[0,1]
	v_pk_mul_f32 v[120:121], v[202:203], v[120:121] op_sel_hi:[0,1]
	v_pk_fma_f32 v[60:61], v[72:73], v[60:61], v[68:69]
	v_pk_fma_f32 v[62:63], v[74:75], v[62:63], v[70:71]
	v_pk_fma_f32 v[64:65], v[64:65], v[120:121], v[76:77]
	v_pk_fma_f32 v[66:67], v[66:67], v[122:123], v[78:79]
	v_pk_fma_f32 v[6:7], v[62:63], s[36:37], v[6:7] op_sel_hi:[1,0,1]
	v_pk_fma_f32 v[4:5], v[60:61], s[36:37], v[4:5] op_sel_hi:[1,0,1]
	v_pk_fma_f32 v[2:3], v[66:67], s[36:37], v[2:3] op_sel_hi:[1,0,1]
	v_pk_fma_f32 v[0:1], v[64:65], s[36:37], v[0:1] op_sel_hi:[1,0,1]
	v_cvt_pk_bf16_f32 v60, v4, v5
	v_cvt_pk_bf16_f32 v61, v6, v7
	v_cvt_pk_bf16_f32 v62, v0, v1
	v_cvt_pk_bf16_f32 v63, v2, v3
	ds_bpermute_b32 v59, v227, v58
	global_store_dwordx4 v[212:213], v[60:63], off offset:256
	s_and_saveexec_b64 s[0:1], s[6:7]
	s_cbranch_execz .LBB0_860
	s_waitcnt lgkmcnt(0)
	v_add_f32_e32 v58, v58, v59
	v_add_f32_e32 v59, v56, v57
	v_lshl_add_u64 v[56:57], s[14:15], 0, v[164:165]
	global_atomic_add_f32 v[56:57], v59, off
	global_atomic_add_f32 v[56:57], v58, off offset:4

.LBB0_1295:
	v_lshl_add_u32 v128, s79, 8, v223
	v_ashrrev_i32_e32 v129, 31, v128
	v_lshlrev_b64 v[164:165], 3, v[128:129]
	v_lshl_add_u64 v[130:131], s[14:15], 0, v[164:165]
	global_load_dwordx2 v[186:187], v[130:131], off
	v_lshl_or_b32 v130, s78, 8, v225
	v_ashrrev_i32_e32 v131, 31, v130
	v_lshlrev_b64 v[132:133], 12, v[128:129]
	v_lshl_add_u64 v[132:133], s[16:17], 0, v[132:133]
	v_lshlrev_b64 v[178:179], 1, v[130:131]
	v_lshl_add_u64 v[176:177], v[132:133], 0, v[178:179]
	global_load_dwordx4 v[192:195], v[176:177], off
	v_or_b32_e32 v196, 16, v128
	v_or_b32_e32 v218, 32, v128
	v_or_b32_e32 v198, 48, v128
	v_add_u32_e32 v204, 0x80, v128
	v_add_u32_e32 v208, 0x90, v128
	v_add_u32_e32 v184, 0xa0, v128
	v_add_u32_e32 v180, 0xb0, v128
	v_lshlrev_b64 v[128:129], 2, v[130:131]
	v_lshl_add_u64 v[188:189], s[68:69], 0, v[128:129]
	v_lshl_add_u64 v[190:191], s[70:71], 0, v[128:129]
	global_load_dwordx4 v[128:131], v[188:189], off offset:16
	global_load_dwordx4 v[136:139], v[188:189], off
	global_load_dwordx4 v[132:135], v[190:191], off offset:16
	global_load_dwordx4 v[140:143], v[190:191], off
	v_ashrrev_i32_e32 v197, 31, v196
	v_ashrrev_i32_e32 v219, 31, v218
	v_ashrrev_i32_e32 v199, 31, v198
	v_ashrrev_i32_e32 v205, 31, v204
	v_ashrrev_i32_e32 v209, 31, v208
	v_ashrrev_i32_e32 v185, 31, v184
	v_ashrrev_i32_e32 v181, 31, v180
	v_lshlrev_b64 v[174:175], 3, v[196:197]
	v_lshlrev_b64 v[172:173], 3, v[218:219]
	v_lshlrev_b64 v[170:171], 3, v[198:199]
	v_lshlrev_b64 v[168:169], 3, v[204:205]
	v_lshlrev_b64 v[166:167], 3, v[208:209]
	v_lshlrev_b64 v[162:163], 3, v[184:185]
	v_lshlrev_b64 v[160:161], 3, v[180:181]
	v_lshl_add_u64 v[182:183], s[14:15], 0, v[174:175]
	v_lshl_add_u64 v[200:201], s[14:15], 0, v[172:173]
	v_lshl_add_u64 v[202:203], s[14:15], 0, v[170:171]
	v_lshl_add_u64 v[210:211], s[14:15], 0, v[168:169]
	v_lshl_add_u64 v[212:213], s[14:15], 0, v[166:167]
	v_lshl_add_u64 v[214:215], s[14:15], 0, v[162:163]
	v_lshl_add_u64 v[216:217], s[14:15], 0, v[160:161]
	global_load_dwordx2 v[230:231], v[182:183], off
	s_nop 0
	global_load_dwordx2 v[200:201], v[200:201], off
	s_nop 0
	global_load_dwordx2 v[206:207], v[202:203], off
	s_nop 0
	global_load_dwordx2 v[210:211], v[210:211], off
	s_nop 0
	global_load_dwordx2 v[212:213], v[212:213], off
	s_nop 0
	global_load_dwordx2 v[182:183], v[214:215], off
	global_load_dwordx2 v[202:203], v[216:217], off
	v_lshlrev_b64 v[198:199], 12, v[198:199]
	v_lshl_add_u64 v[198:199], s[16:17], 0, v[198:199]
	v_lshl_add_u64 v[198:199], v[198:199], 0, v[178:179]
	v_lshlrev_b64 v[204:205], 12, v[204:205]
	v_lshl_add_u64 v[204:205], s[16:17], 0, v[204:205]
	v_lshl_add_u64 v[204:205], v[204:205], 0, v[178:179]
	v_lshlrev_b64 v[208:209], 12, v[208:209]
	v_lshl_add_u64 v[208:209], s[16:17], 0, v[208:209]
	v_lshl_add_u64 v[208:209], v[208:209], 0, v[178:179]
	v_lshlrev_b64 v[184:185], 12, v[184:185]
	v_lshl_add_u64 v[184:185], s[16:17], 0, v[184:185]
	v_lshlrev_b64 v[180:181], 12, v[180:181]
	v_lshl_add_u64 v[180:181], s[16:17], 0, v[180:181]
	s_waitcnt vmcnt(0)
	v_pk_mul_f32 v[186:187], v[186:187], s[30:31] op_sel:[1,0] op_sel_hi:[0,0]
	v_fma_f32 v186, -v187, v187, v186
	v_max_f32_e32 v186, 0, v186
	v_add_f32_e32 v186, 0x3727c5ac, v186
	v_cmp_gt_f32_e32 vcc, s63, v186
	v_lshlrev_b32_e32 v214, 16, v192
	v_and_b32_e32 v192, 0xffff0000, v192
	v_lshlrev_b32_e32 v215, 16, v193
	v_and_b32_e32 v216, 0xffff0000, v193
	v_sub_f32_e32 v193, v192, v187
	v_sub_f32_e32 v192, v214, v187
	v_mul_f32_e32 v214, 0x4f800000, v186
	v_cndmask_b32_e32 v186, v186, v214, vcc
	v_lshlrev_b32_e32 v233, 16, v195
	v_and_b32_e32 v234, 0xffff0000, v195
	v_sub_f32_e32 v195, v216, v187
	v_sqrt_f32_e32 v216, v186
	v_and_b32_e32 v232, 0xffff0000, v194
	v_lshlrev_b32_e32 v217, 16, v194
	v_sub_f32_e32 v194, v215, v187
	v_sub_f32_e32 v215, v232, v187
	v_add_u32_e32 v232, -1, v216
	v_sub_f32_e32 v214, v217, v187
	v_sub_f32_e32 v217, v234, v187
	v_add_u32_e32 v234, 1, v216
	v_fma_f32 v235, -v232, v216, v186
	v_fma_f32 v236, -v234, v216, v186
	v_cmp_ge_f32_e64 s[0:1], 0, v235
	v_pk_mul_f32 v[200:201], v[200:201], s[30:31] op_sel:[1,0] op_sel_hi:[0,0]
	s_nop 0
	v_cndmask_b32_e64 v216, v216, v232, s[0:1]
	v_cmp_lt_f32_e64 s[0:1], 0, v236
	v_fma_f32 v200, -v201, v201, v200
	v_max_f32_e32 v200, 0, v200
	v_cndmask_b32_e64 v216, v216, v234, s[0:1]
	v_mul_f32_e32 v232, 0x37800000, v216
	v_cndmask_b32_e32 v216, v216, v232, vcc
	v_cmp_class_f32_e32 vcc, v186, v229
	v_add_f32_e32 v200, 0x3727c5ac, v200
	v_pk_mul_f32 v[206:207], v[206:207], s[30:31] op_sel:[1,0] op_sel_hi:[0,0]
	v_cndmask_b32_e32 v186, v216, v186, vcc
	v_div_scale_f32 v232, s[0:1], v186, v186, 1.0
	v_rcp_f32_e32 v234, v232
	v_sub_f32_e32 v216, v233, v187
	v_div_scale_f32 v233, vcc, 1.0, v186, 1.0
	v_fma_f32 v235, -v232, v234, 1.0
	v_fmac_f32_e32 v234, v235, v234
	v_mul_f32_e32 v235, v233, v234
	v_fma_f32 v236, -v232, v235, v233
	v_fmac_f32_e32 v235, v236, v234
	v_fma_f32 v232, -v232, v235, v233
	v_div_fmas_f32 v232, v232, v234, v235
	v_div_fixup_f32 v186, v232, v186, 1.0
	v_pk_mul_f32 v[194:195], v[186:187], v[194:195] op_sel_hi:[0,1]
	v_pk_mul_f32 v[192:193], v[186:187], v[192:193] op_sel_hi:[0,1]
	v_pk_mul_f32 v[216:217], v[186:187], v[216:217] op_sel_hi:[0,1]
	v_pk_mul_f32 v[214:215], v[186:187], v[214:215] op_sel_hi:[0,1]
	v_pk_fma_f32 v[192:193], v[136:137], v[192:193], v[140:141]
	v_pk_fma_f32 v[194:195], v[138:139], v[194:195], v[142:143]
	v_pk_fma_f32 v[214:215], v[128:129], v[214:215], v[132:133]
	v_pk_fma_f32 v[216:217], v[130:131], v[216:217], v[134:135]
	v_pk_fma_f32 v[126:127], v[194:195], s[34:35], v[126:127] op_sel_hi:[1,0,1]
	v_pk_fma_f32 v[124:125], v[192:193], s[34:35], v[124:125] op_sel_hi:[1,0,1]
	v_pk_fma_f32 v[122:123], v[216:217], s[34:35], v[122:123] op_sel_hi:[1,0,1]
	v_pk_fma_f32 v[120:121], v[214:215], s[34:35], v[120:121] op_sel_hi:[1,0,1]
	v_cvt_pk_bf16_f32 v192, v124, v125
	v_cvt_pk_bf16_f32 v193, v126, v127
	v_cvt_pk_bf16_f32 v194, v120, v121
	v_cvt_pk_bf16_f32 v195, v122, v123
	global_store_dwordx4 v[176:177], v[192:195], off
	v_fma_f32 v206, -v207, v207, v206
	v_max_f32_e32 v206, 0, v206
	v_lshlrev_b64 v[192:193], 12, v[196:197]
	v_lshl_add_u64 v[192:193], s[16:17], 0, v[192:193]
	v_lshl_add_u64 v[192:193], v[192:193], 0, v[178:179]
	global_load_dwordx4 v[214:217], v[192:193], off
	v_pk_mul_f32 v[196:197], v[230:231], s[30:31] op_sel:[1,0] op_sel_hi:[0,0]
	v_fma_f32 v194, -v197, v197, v196
	v_max_f32_e32 v194, 0, v194
	v_add_f32_e32 v194, 0x3727c5ac, v194
	v_mul_f32_e32 v195, 0x4f800000, v194
	v_cmp_gt_f32_e32 vcc, s63, v194
	v_add_f32_e32 v206, 0x3727c5ac, v206
	v_pk_mul_f32 v[210:211], v[210:211], s[30:31] op_sel:[1,0] op_sel_hi:[0,0]
	v_cndmask_b32_e32 v196, v194, v195, vcc
	v_sqrt_f32_e32 v230, v196
	v_lshlrev_b64 v[194:195], 12, v[218:219]
	v_lshl_add_u64 v[194:195], s[16:17], 0, v[194:195]
	v_lshl_add_u64 v[194:195], v[194:195], 0, v[178:179]
	v_add_u32_e32 v218, -1, v230
	v_add_u32_e32 v219, 1, v230
	v_fma_f32 v231, -v218, v230, v196
	v_fma_f32 v232, -v219, v230, v196
	v_cmp_ge_f32_e64 s[0:1], 0, v231
	v_fma_f32 v210, -v211, v211, v210
	v_max_f32_e32 v210, 0, v210
	v_cndmask_b32_e64 v218, v230, v218, s[0:1]
	v_cmp_lt_f32_e64 s[0:1], 0, v232
	v_add_f32_e32 v210, 0x3727c5ac, v210
	v_pk_mul_f32 v[202:203], v[202:203], s[30:31] op_sel:[1,0] op_sel_hi:[0,0]
	v_cndmask_b32_e64 v218, v218, v219, s[0:1]
	v_mul_f32_e32 v219, 0x37800000, v218
	v_cndmask_b32_e32 v218, v218, v219, vcc
	v_cmp_class_f32_e32 vcc, v196, v229
	s_waitcnt vmcnt(0)
	v_lshlrev_b32_e32 v233, 16, v217
	v_cndmask_b32_e32 v196, v218, v196, vcc
	v_div_scale_f32 v218, s[0:1], v196, v196, 1.0
	v_rcp_f32_e32 v219, v218
	v_div_scale_f32 v230, vcc, 1.0, v196, 1.0
	v_and_b32_e32 v234, 0xffff0000, v217
	v_fma_f32 v231, -v218, v219, 1.0
	v_fmac_f32_e32 v219, v231, v219
	v_mul_f32_e32 v231, v230, v219
	v_fma_f32 v232, -v218, v231, v230
	v_fmac_f32_e32 v231, v232, v219
	v_fma_f32 v218, -v218, v231, v230
	v_div_fmas_f32 v218, v218, v219, v231
	v_div_fixup_f32 v196, v218, v196, 1.0
	v_lshlrev_b32_e32 v218, 16, v214
	v_and_b32_e32 v214, 0xffff0000, v214
	v_lshlrev_b32_e32 v219, 16, v215
	v_and_b32_e32 v230, 0xffff0000, v215
	v_lshlrev_b32_e32 v231, 16, v216
	v_and_b32_e32 v232, 0xffff0000, v216
	v_sub_f32_e32 v215, v214, v197
	v_sub_f32_e32 v214, v218, v197
	v_sub_f32_e32 v217, v230, v197
	v_sub_f32_e32 v216, v219, v197
	v_sub_f32_e32 v219, v232, v197
	v_sub_f32_e32 v218, v231, v197
	v_sub_f32_e32 v231, v234, v197
	v_sub_f32_e32 v230, v233, v197
	v_pk_mul_f32 v[216:217], v[196:197], v[216:217] op_sel_hi:[0,1]
	v_pk_mul_f32 v[214:215], v[196:197], v[214:215] op_sel_hi:[0,1]
	v_pk_mul_f32 v[230:231], v[196:197], v[230:231] op_sel_hi:[0,1]
	v_pk_mul_f32 v[218:219], v[196:197], v[218:219] op_sel_hi:[0,1]
	v_pk_fma_f32 v[214:215], v[136:137], v[214:215], v[140:141]
	v_pk_fma_f32 v[216:217], v[138:139], v[216:217], v[142:143]
	v_pk_fma_f32 v[218:219], v[128:129], v[218:219], v[132:133]
	v_pk_fma_f32 v[230:231], v[130:131], v[230:231], v[134:135]
	v_pk_fma_f32 v[118:119], v[216:217], s[34:35], v[118:119] op_sel_hi:[1,0,1]
	v_pk_fma_f32 v[116:117], v[214:215], s[34:35], v[116:117] op_sel_hi:[1,0,1]
	v_pk_fma_f32 v[114:115], v[230:231], s[34:35], v[114:115] op_sel_hi:[1,0,1]
	v_pk_fma_f32 v[112:113], v[218:219], s[34:35], v[112:113] op_sel_hi:[1,0,1]
	v_cvt_pk_bf16_f32 v214, v116, v117
	v_cvt_pk_bf16_f32 v215, v118, v119
	v_cvt_pk_bf16_f32 v216, v112, v113
	v_cvt_pk_bf16_f32 v217, v114, v115
	global_store_dwordx4 v[192:193], v[214:217], off
	global_load_dwordx4 v[214:217], v[194:195], off
	v_mul_f32_e32 v218, 0x4f800000, v200
	v_cmp_gt_f32_e32 vcc, s63, v200
	s_waitcnt vmcnt(0)
	v_lshlrev_b32_e32 v233, 16, v217
	v_cndmask_b32_e32 v200, v200, v218, vcc
	v_sqrt_f32_e32 v218, v200
	v_and_b32_e32 v234, 0xffff0000, v217
	v_add_u32_e32 v219, -1, v218
	v_add_u32_e32 v230, 1, v218
	v_fma_f32 v231, -v219, v218, v200
	v_fma_f32 v232, -v230, v218, v200
	v_cmp_ge_f32_e64 s[0:1], 0, v231
	s_nop 1
	v_cndmask_b32_e64 v218, v218, v219, s[0:1]
	v_cmp_lt_f32_e64 s[0:1], 0, v232
	s_nop 1
	v_cndmask_b32_e64 v218, v218, v230, s[0:1]
	v_mul_f32_e32 v219, 0x37800000, v218
	v_cndmask_b32_e32 v218, v218, v219, vcc
	v_cmp_class_f32_e32 vcc, v200, v229
	s_nop 1
	v_cndmask_b32_e32 v200, v218, v200, vcc
	v_div_scale_f32 v218, s[0:1], v200, v200, 1.0
	v_rcp_f32_e32 v219, v218
	v_div_scale_f32 v230, vcc, 1.0, v200, 1.0
	v_fma_f32 v231, -v218, v219, 1.0
	v_fmac_f32_e32 v219, v231, v219
	v_mul_f32_e32 v231, v230, v219
	v_fma_f32 v232, -v218, v231, v230
	v_fmac_f32_e32 v231, v232, v219
	v_fma_f32 v218, -v218, v231, v230
	v_div_fmas_f32 v218, v218, v219, v231
	v_div_fixup_f32 v200, v218, v200, 1.0
	v_lshlrev_b32_e32 v218, 16, v214
	v_and_b32_e32 v214, 0xffff0000, v214
	v_lshlrev_b32_e32 v219, 16, v215
	v_and_b32_e32 v230, 0xffff0000, v215
	v_lshlrev_b32_e32 v231, 16, v216
	v_and_b32_e32 v232, 0xffff0000, v216
	v_sub_f32_e32 v215, v214, v201
	v_sub_f32_e32 v214, v218, v201
	v_sub_f32_e32 v217, v230, v201
	v_sub_f32_e32 v216, v219, v201
	v_sub_f32_e32 v219, v232, v201
	v_sub_f32_e32 v218, v231, v201
	v_sub_f32_e32 v231, v234, v201
	v_sub_f32_e32 v230, v233, v201
	v_pk_mul_f32 v[216:217], v[200:201], v[216:217] op_sel_hi:[0,1]
	v_pk_mul_f32 v[214:215], v[200:201], v[214:215] op_sel_hi:[0,1]
	v_pk_mul_f32 v[230:231], v[200:201], v[230:231] op_sel_hi:[0,1]
	v_pk_mul_f32 v[218:219], v[200:201], v[218:219] op_sel_hi:[0,1]
	v_pk_fma_f32 v[214:215], v[136:137], v[214:215], v[140:141]
	v_pk_fma_f32 v[216:217], v[138:139], v[216:217], v[142:143]
	v_pk_fma_f32 v[218:219], v[128:129], v[218:219], v[132:133]
	v_pk_fma_f32 v[230:231], v[130:131], v[230:231], v[134:135]
	v_pk_fma_f32 v[110:111], v[216:217], s[34:35], v[110:111] op_sel_hi:[1,0,1]
	v_pk_fma_f32 v[108:109], v[214:215], s[34:35], v[108:109] op_sel_hi:[1,0,1]
	v_pk_fma_f32 v[106:107], v[230:231], s[34:35], v[106:107] op_sel_hi:[1,0,1]
	v_pk_fma_f32 v[104:105], v[218:219], s[34:35], v[104:105] op_sel_hi:[1,0,1]
	v_cvt_pk_bf16_f32 v214, v108, v109
	v_cvt_pk_bf16_f32 v215, v110, v111
	v_cvt_pk_bf16_f32 v216, v104, v105
	v_cvt_pk_bf16_f32 v217, v106, v107
	global_store_dwordx4 v[194:195], v[214:217], off
	global_load_dwordx4 v[214:217], v[198:199], off
	v_mul_f32_e32 v218, 0x4f800000, v206
	v_cmp_gt_f32_e32 vcc, s63, v206
	s_waitcnt vmcnt(0)
	v_lshlrev_b32_e32 v233, 16, v217
	v_cndmask_b32_e32 v206, v206, v218, vcc
	v_sqrt_f32_e32 v218, v206
	v_and_b32_e32 v234, 0xffff0000, v217
	v_add_u32_e32 v219, -1, v218
	v_add_u32_e32 v230, 1, v218
	v_fma_f32 v231, -v219, v218, v206
	v_fma_f32 v232, -v230, v218, v206
	v_cmp_ge_f32_e64 s[0:1], 0, v231
	s_nop 1
	v_cndmask_b32_e64 v218, v218, v219, s[0:1]
	v_cmp_lt_f32_e64 s[0:1], 0, v232
	s_nop 1
	v_cndmask_b32_e64 v218, v218, v230, s[0:1]
	v_mul_f32_e32 v219, 0x37800000, v218
	v_cndmask_b32_e32 v218, v218, v219, vcc
	v_cmp_class_f32_e32 vcc, v206, v229
	s_nop 1
	v_cndmask_b32_e32 v206, v218, v206, vcc
	v_div_scale_f32 v218, s[0:1], v206, v206, 1.0
	v_rcp_f32_e32 v219, v218
	v_div_scale_f32 v230, vcc, 1.0, v206, 1.0
	v_fma_f32 v231, -v218, v219, 1.0
	v_fmac_f32_e32 v219, v231, v219
	v_mul_f32_e32 v231, v230, v219
	v_fma_f32 v232, -v218, v231, v230
	v_fmac_f32_e32 v231, v232, v219
	v_fma_f32 v218, -v218, v231, v230
	v_div_fmas_f32 v218, v218, v219, v231
	v_div_fixup_f32 v206, v218, v206, 1.0
	v_lshlrev_b32_e32 v218, 16, v214
	v_and_b32_e32 v214, 0xffff0000, v214
	v_lshlrev_b32_e32 v219, 16, v215
	v_and_b32_e32 v230, 0xffff0000, v215
	v_lshlrev_b32_e32 v231, 16, v216
	v_and_b32_e32 v232, 0xffff0000, v216
	v_sub_f32_e32 v215, v214, v207
	v_sub_f32_e32 v214, v218, v207
	v_sub_f32_e32 v217, v230, v207
	v_sub_f32_e32 v216, v219, v207
	v_sub_f32_e32 v219, v232, v207
	v_sub_f32_e32 v218, v231, v207
	v_sub_f32_e32 v231, v234, v207
	v_sub_f32_e32 v230, v233, v207
	v_pk_mul_f32 v[216:217], v[206:207], v[216:217] op_sel_hi:[0,1]
	v_pk_mul_f32 v[214:215], v[206:207], v[214:215] op_sel_hi:[0,1]
	v_pk_mul_f32 v[230:231], v[206:207], v[230:231] op_sel_hi:[0,1]
	v_pk_mul_f32 v[218:219], v[206:207], v[218:219] op_sel_hi:[0,1]
	v_pk_fma_f32 v[214:215], v[136:137], v[214:215], v[140:141]
	v_pk_fma_f32 v[216:217], v[138:139], v[216:217], v[142:143]
	v_pk_fma_f32 v[218:219], v[128:129], v[218:219], v[132:133]
	v_pk_fma_f32 v[230:231], v[130:131], v[230:231], v[134:135]
	v_pk_fma_f32 v[102:103], v[216:217], s[34:35], v[102:103] op_sel_hi:[1,0,1]
	v_pk_fma_f32 v[100:101], v[214:215], s[34:35], v[100:101] op_sel_hi:[1,0,1]
	v_pk_fma_f32 v[98:99], v[230:231], s[34:35], v[98:99] op_sel_hi:[1,0,1]
	v_pk_fma_f32 v[96:97], v[218:219], s[34:35], v[96:97] op_sel_hi:[1,0,1]
	v_cvt_pk_bf16_f32 v214, v100, v101
	v_cvt_pk_bf16_f32 v215, v102, v103
	v_cvt_pk_bf16_f32 v216, v96, v97
	v_cvt_pk_bf16_f32 v217, v98, v99
	global_store_dwordx4 v[198:199], v[214:217], off
	global_load_dwordx4 v[214:217], v[204:205], off
	v_mul_f32_e32 v218, 0x4f800000, v210
	v_cmp_gt_f32_e32 vcc, s63, v210
	s_waitcnt vmcnt(0)
	v_lshlrev_b32_e32 v233, 16, v217
	v_cndmask_b32_e32 v210, v210, v218, vcc
	v_sqrt_f32_e32 v218, v210
	v_and_b32_e32 v234, 0xffff0000, v217
	v_add_u32_e32 v219, -1, v218
	v_add_u32_e32 v230, 1, v218
	v_fma_f32 v231, -v219, v218, v210
	v_fma_f32 v232, -v230, v218, v210
	v_cmp_ge_f32_e64 s[0:1], 0, v231
	s_nop 1
	v_cndmask_b32_e64 v218, v218, v219, s[0:1]
	v_cmp_lt_f32_e64 s[0:1], 0, v232
	s_nop 1
	v_cndmask_b32_e64 v218, v218, v230, s[0:1]
	v_mul_f32_e32 v219, 0x37800000, v218
	v_cndmask_b32_e32 v218, v218, v219, vcc
	v_cmp_class_f32_e32 vcc, v210, v229
	s_nop 1
	v_cndmask_b32_e32 v210, v218, v210, vcc
	v_div_scale_f32 v218, s[0:1], v210, v210, 1.0
	v_rcp_f32_e32 v219, v218
	v_div_scale_f32 v230, vcc, 1.0, v210, 1.0
	v_fma_f32 v231, -v218, v219, 1.0
	v_fmac_f32_e32 v219, v231, v219
	v_mul_f32_e32 v231, v230, v219
	v_fma_f32 v232, -v218, v231, v230
	v_fmac_f32_e32 v231, v232, v219
	v_fma_f32 v218, -v218, v231, v230
	v_div_fmas_f32 v218, v218, v219, v231
	v_div_fixup_f32 v210, v218, v210, 1.0
	v_lshlrev_b32_e32 v218, 16, v214
	v_and_b32_e32 v214, 0xffff0000, v214
	v_lshlrev_b32_e32 v219, 16, v215
	v_and_b32_e32 v230, 0xffff0000, v215
	v_lshlrev_b32_e32 v231, 16, v216
	v_and_b32_e32 v232, 0xffff0000, v216
	v_sub_f32_e32 v215, v214, v211
	v_sub_f32_e32 v214, v218, v211
	v_sub_f32_e32 v217, v230, v211
	v_sub_f32_e32 v216, v219, v211
	v_sub_f32_e32 v219, v232, v211
	v_sub_f32_e32 v218, v231, v211
	v_sub_f32_e32 v231, v234, v211
	v_sub_f32_e32 v230, v233, v211
	v_pk_mul_f32 v[216:217], v[210:211], v[216:217] op_sel_hi:[0,1]
	v_pk_mul_f32 v[214:215], v[210:211], v[214:215] op_sel_hi:[0,1]
	v_pk_mul_f32 v[230:231], v[210:211], v[230:231] op_sel_hi:[0,1]
	v_pk_mul_f32 v[218:219], v[210:211], v[218:219] op_sel_hi:[0,1]
	v_pk_fma_f32 v[214:215], v[136:137], v[214:215], v[140:141]
	v_pk_fma_f32 v[216:217], v[138:139], v[216:217], v[142:143]
	v_pk_fma_f32 v[218:219], v[128:129], v[218:219], v[132:133]
	v_pk_fma_f32 v[230:231], v[130:131], v[230:231], v[134:135]
	v_pk_fma_f32 v[94:95], v[216:217], s[34:35], v[94:95] op_sel_hi:[1,0,1]
	v_pk_fma_f32 v[92:93], v[214:215], s[34:35], v[92:93] op_sel_hi:[1,0,1]
	v_pk_fma_f32 v[90:91], v[230:231], s[34:35], v[90:91] op_sel_hi:[1,0,1]
	v_pk_fma_f32 v[88:89], v[218:219], s[34:35], v[88:89] op_sel_hi:[1,0,1]
	v_cvt_pk_bf16_f32 v214, v92, v93
	v_cvt_pk_bf16_f32 v215, v94, v95
	v_cvt_pk_bf16_f32 v216, v88, v89
	v_cvt_pk_bf16_f32 v217, v90, v91
	global_store_dwordx4 v[204:205], v[214:217], off
	global_load_dwordx4 v[230:233], v[208:209], off
	s_waitcnt vmcnt(0)
	v_and_b32_e32 v219, 0xffff0000, v232
	v_pk_mul_f32 v[216:217], v[212:213], s[30:31] op_sel:[1,0] op_sel_hi:[0,0]
	v_fma_f32 v212, -v217, v217, v216
	v_max_f32_e32 v212, 0, v212
	v_add_f32_e32 v212, 0x3727c5ac, v212
	v_mul_f32_e32 v213, 0x4f800000, v212
	v_cmp_gt_f32_e32 vcc, s63, v212
	v_sub_f32_e32 v219, v219, v217
	s_nop 0
	v_cndmask_b32_e32 v212, v212, v213, vcc
	v_sqrt_f32_e32 v213, v212
	s_nop 0
	v_add_u32_e32 v214, -1, v213
	v_add_u32_e32 v215, 1, v213
	v_fma_f32 v216, -v214, v213, v212
	v_fma_f32 v218, -v215, v213, v212
	v_cmp_ge_f32_e64 s[0:1], 0, v216
	s_nop 1
	v_cndmask_b32_e64 v213, v213, v214, s[0:1]
	v_cmp_lt_f32_e64 s[0:1], 0, v218
	s_nop 1
	v_cndmask_b32_e64 v213, v213, v215, s[0:1]
	v_mul_f32_e32 v214, 0x37800000, v213
	v_cndmask_b32_e32 v213, v213, v214, vcc
	v_cmp_class_f32_e32 vcc, v212, v229
	v_lshl_add_u64 v[214:215], v[184:185], 0, v[178:179]
	s_nop 0
	v_cndmask_b32_e32 v212, v213, v212, vcc
	v_div_scale_f32 v213, s[0:1], v212, v212, 1.0
	v_rcp_f32_e32 v216, v213
	v_div_scale_f32 v184, vcc, 1.0, v212, 1.0
	v_fma_f32 v185, -v213, v216, 1.0
	v_fmac_f32_e32 v216, v185, v216
	v_mul_f32_e32 v185, v184, v216
	v_fma_f32 v218, -v213, v185, v184
	v_fmac_f32_e32 v185, v218, v216
	v_fma_f32 v184, -v213, v185, v184
	v_div_fmas_f32 v184, v184, v216, v185
	v_div_fixup_f32 v216, v184, v212, 1.0
	v_lshlrev_b32_e32 v184, 16, v230
	v_and_b32_e32 v185, 0xffff0000, v230
	v_lshlrev_b32_e32 v212, 16, v231
	v_and_b32_e32 v213, 0xffff0000, v231
	v_lshlrev_b32_e32 v218, 16, v232
	v_lshlrev_b32_e32 v230, 16, v233
	v_and_b32_e32 v231, 0xffff0000, v233
	v_sub_f32_e32 v185, v185, v217
	v_sub_f32_e32 v184, v184, v217
	v_sub_f32_e32 v213, v213, v217
	v_sub_f32_e32 v212, v212, v217
	v_sub_f32_e32 v218, v218, v217
	v_sub_f32_e32 v231, v231, v217
	v_sub_f32_e32 v230, v230, v217
	v_pk_mul_f32 v[212:213], v[216:217], v[212:213] op_sel_hi:[0,1]
	v_pk_mul_f32 v[184:185], v[216:217], v[184:185] op_sel_hi:[0,1]
	v_pk_mul_f32 v[230:231], v[216:217], v[230:231] op_sel_hi:[0,1]
	v_pk_mul_f32 v[218:219], v[216:217], v[218:219] op_sel_hi:[0,1]
	v_pk_fma_f32 v[184:185], v[136:137], v[184:185], v[140:141]
	v_pk_fma_f32 v[212:213], v[138:139], v[212:213], v[142:143]
	v_pk_fma_f32 v[218:219], v[128:129], v[218:219], v[132:133]
	v_pk_fma_f32 v[230:231], v[130:131], v[230:231], v[134:135]
	v_pk_fma_f32 v[86:87], v[212:213], s[34:35], v[86:87] op_sel_hi:[1,0,1]
	v_pk_fma_f32 v[84:85], v[184:185], s[34:35], v[84:85] op_sel_hi:[1,0,1]
	v_pk_fma_f32 v[82:83], v[230:231], s[34:35], v[82:83] op_sel_hi:[1,0,1]
	v_pk_fma_f32 v[80:81], v[218:219], s[34:35], v[80:81] op_sel_hi:[1,0,1]
	v_cvt_pk_bf16_f32 v230, v84, v85
	v_cvt_pk_bf16_f32 v231, v86, v87
	v_cvt_pk_bf16_f32 v232, v80, v81
	v_cvt_pk_bf16_f32 v233, v82, v83
	global_store_dwordx4 v[208:209], v[230:233], off
	global_load_dwordx4 v[230:233], v[214:215], off
	v_pk_mul_f32 v[218:219], v[182:183], s[30:31] op_sel:[1,0] op_sel_hi:[0,0]
	v_fma_f32 v182, -v219, v219, v218
	v_max_f32_e32 v182, 0, v182
	v_add_f32_e32 v182, 0x3727c5ac, v182
	v_mul_f32_e32 v183, 0x4f800000, v182
	v_cmp_gt_f32_e32 vcc, s63, v182
	s_nop 1
	v_cndmask_b32_e32 v182, v182, v183, vcc
	v_sqrt_f32_e32 v183, v182
	s_nop 0
	v_add_u32_e32 v184, -1, v183
	v_add_u32_e32 v185, 1, v183
	v_fma_f32 v212, -v184, v183, v182
	v_fma_f32 v213, -v185, v183, v182
	v_cmp_ge_f32_e64 s[0:1], 0, v212
	s_nop 1
	v_cndmask_b32_e64 v183, v183, v184, s[0:1]
	v_cmp_lt_f32_e64 s[0:1], 0, v213
	v_lshl_add_u64 v[212:213], v[180:181], 0, v[178:179]
	s_waitcnt vmcnt(0)
	v_and_b32_e32 v181, 0xffff0000, v231
	v_cndmask_b32_e64 v183, v183, v185, s[0:1]
	v_mul_f32_e32 v184, 0x37800000, v183
	v_cndmask_b32_e32 v183, v183, v184, vcc
	v_cmp_class_f32_e32 vcc, v182, v229
	v_and_b32_e32 v185, 0xffff0000, v233
	v_sub_f32_e32 v181, v181, v219
	v_cndmask_b32_e32 v182, v183, v182, vcc
	v_div_scale_f32 v183, s[0:1], v182, v182, 1.0
	v_rcp_f32_e32 v184, v183
	v_div_scale_f32 v178, vcc, 1.0, v182, 1.0
	v_sub_f32_e32 v185, v185, v219
	v_fma_f32 v179, -v183, v184, 1.0
	v_fmac_f32_e32 v184, v179, v184
	v_mul_f32_e32 v179, v178, v184
	v_fma_f32 v180, -v183, v179, v178
	v_fmac_f32_e32 v179, v180, v184
	v_fma_f32 v178, -v183, v179, v178
	v_div_fmas_f32 v178, v178, v184, v179
	v_div_fixup_f32 v218, v178, v182, 1.0
	v_lshlrev_b32_e32 v178, 16, v230
	v_and_b32_e32 v179, 0xffff0000, v230
	v_lshlrev_b32_e32 v180, 16, v231
	v_lshlrev_b32_e32 v182, 16, v232
	v_and_b32_e32 v183, 0xffff0000, v232
	v_lshlrev_b32_e32 v184, 16, v233
	v_sub_f32_e32 v179, v179, v219
	v_sub_f32_e32 v178, v178, v219
	v_sub_f32_e32 v180, v180, v219
	v_sub_f32_e32 v183, v183, v219
	v_sub_f32_e32 v182, v182, v219
	v_sub_f32_e32 v184, v184, v219
	v_pk_mul_f32 v[180:181], v[218:219], v[180:181] op_sel_hi:[0,1]
	v_pk_mul_f32 v[178:179], v[218:219], v[178:179] op_sel_hi:[0,1]
	v_pk_mul_f32 v[184:185], v[218:219], v[184:185] op_sel_hi:[0,1]
	v_pk_mul_f32 v[182:183], v[218:219], v[182:183] op_sel_hi:[0,1]
	v_pk_fma_f32 v[178:179], v[136:137], v[178:179], v[140:141]
	v_pk_fma_f32 v[180:181], v[138:139], v[180:181], v[142:143]
	v_pk_fma_f32 v[230:231], v[128:129], v[182:183], v[132:133]
	v_pk_fma_f32 v[232:233], v[130:131], v[184:185], v[134:135]
	v_pk_fma_f32 v[182:183], v[180:181], s[34:35], v[78:79] op_sel_hi:[1,0,1]
	v_pk_fma_f32 v[184:185], v[178:179], s[34:35], v[76:77] op_sel_hi:[1,0,1]
	v_pk_fma_f32 v[178:179], v[232:233], s[34:35], v[74:75] op_sel_hi:[1,0,1]
	v_pk_fma_f32 v[180:181], v[230:231], s[34:35], v[72:73] op_sel_hi:[1,0,1]
	v_cvt_pk_bf16_f32 v72, v184, v185
	v_cvt_pk_bf16_f32 v73, v182, v183
	v_cvt_pk_bf16_f32 v74, v180, v181
	v_cvt_pk_bf16_f32 v75, v178, v179
	global_store_dwordx4 v[214:215], v[72:75], off
	global_load_dwordx4 v[72:75], v[212:213], off
	v_fma_f32 v76, -v203, v203, v202
	v_max_f32_e32 v76, 0, v76
	v_add_f32_e32 v76, 0x3727c5ac, v76
	v_mul_f32_e32 v77, 0x4f800000, v76
	v_cmp_gt_f32_e32 vcc, s63, v76
	s_waitcnt vmcnt(0)
	v_lshlrev_b32_e32 v231, 16, v75
	v_cndmask_b32_e32 v76, v76, v77, vcc
	v_sqrt_f32_e32 v77, v76
	v_and_b32_e32 v232, 0xffff0000, v75
	v_add_u32_e32 v78, -1, v77
	v_add_u32_e32 v79, 1, v77
	v_fma_f32 v202, -v78, v77, v76
	v_fma_f32 v230, -v79, v77, v76
	v_cmp_ge_f32_e64 s[0:1], 0, v202
	s_nop 1
	v_cndmask_b32_e64 v77, v77, v78, s[0:1]
	v_cmp_lt_f32_e64 s[0:1], 0, v230
	s_nop 1
	v_cndmask_b32_e64 v77, v77, v79, s[0:1]
	v_mul_f32_e32 v78, 0x37800000, v77
	v_cndmask_b32_e32 v77, v77, v78, vcc
	v_cmp_class_f32_e32 vcc, v76, v229
	s_nop 1
	v_cndmask_b32_e32 v76, v77, v76, vcc
	v_div_scale_f32 v77, s[0:1], v76, v76, 1.0
	v_rcp_f32_e32 v78, v77
	v_div_scale_f32 v79, vcc, 1.0, v76, 1.0
	v_fma_f32 v202, -v77, v78, 1.0
	v_fmac_f32_e32 v78, v202, v78
	v_mul_f32_e32 v202, v79, v78
	v_fma_f32 v230, -v77, v202, v79
	v_fmac_f32_e32 v202, v230, v78
	v_fma_f32 v77, -v77, v202, v79
	v_div_fmas_f32 v77, v77, v78, v202
	v_div_fixup_f32 v202, v77, v76, 1.0
	v_lshlrev_b32_e32 v76, 16, v72
	v_and_b32_e32 v72, 0xffff0000, v72
	v_lshlrev_b32_e32 v77, 16, v73
	v_and_b32_e32 v78, 0xffff0000, v73
	v_lshlrev_b32_e32 v79, 16, v74
	v_and_b32_e32 v230, 0xffff0000, v74
	v_sub_f32_e32 v73, v72, v203
	v_sub_f32_e32 v72, v76, v203
	v_sub_f32_e32 v75, v78, v203
	v_sub_f32_e32 v74, v77, v203
	v_sub_f32_e32 v77, v230, v203
	v_sub_f32_e32 v76, v79, v203
	v_sub_f32_e32 v79, v232, v203
	v_sub_f32_e32 v78, v231, v203
	v_pk_mul_f32 v[74:75], v[202:203], v[74:75] op_sel_hi:[0,1]
	v_pk_mul_f32 v[72:73], v[202:203], v[72:73] op_sel_hi:[0,1]
	v_pk_mul_f32 v[78:79], v[202:203], v[78:79] op_sel_hi:[0,1]
	v_pk_mul_f32 v[76:77], v[202:203], v[76:77] op_sel_hi:[0,1]
	v_pk_fma_f32 v[72:73], v[136:137], v[72:73], v[140:141]
	v_pk_fma_f32 v[74:75], v[138:139], v[74:75], v[142:143]
	v_pk_fma_f32 v[76:77], v[128:129], v[76:77], v[132:133]
	v_pk_fma_f32 v[78:79], v[130:131], v[78:79], v[134:135]
	v_pk_fma_f32 v[130:131], v[74:75], s[34:35], v[70:71] op_sel_hi:[1,0,1]
	v_pk_fma_f32 v[134:135], v[72:73], s[34:35], v[68:69] op_sel_hi:[1,0,1]
	v_pk_fma_f32 v[128:129], v[78:79], s[34:35], v[66:67] op_sel_hi:[1,0,1]
	v_pk_fma_f32 v[132:133], v[76:77], s[34:35], v[64:65] op_sel_hi:[1,0,1]
	v_cvt_pk_bf16_f32 v64, v134, v135
	v_cvt_pk_bf16_f32 v65, v130, v131
	v_cvt_pk_bf16_f32 v66, v132, v133
	v_cvt_pk_bf16_f32 v67, v128, v129
	global_store_dwordx4 v[212:213], v[64:67], off
	global_load_dwordx4 v[136:139], v[176:177], off offset:256
	global_load_dwordx4 v[68:71], v[190:191], off offset:512
	global_load_dwordx4 v[72:75], v[188:189], off offset:512
	global_load_dwordx4 v[64:67], v[188:189], off offset:528
	global_load_dwordx4 v[76:79], v[190:191], off offset:528
	s_waitcnt vmcnt(0)
	v_lshlrev_b32_e32 v140, 16, v136
	v_and_b32_e32 v136, 0xffff0000, v136
	v_lshlrev_b32_e32 v141, 16, v137
	v_and_b32_e32 v142, 0xffff0000, v137
	v_lshlrev_b32_e32 v143, 16, v138
	v_and_b32_e32 v188, 0xffff0000, v138
	v_lshlrev_b32_e32 v189, 16, v139
	v_and_b32_e32 v190, 0xffff0000, v139
	v_sub_f32_e32 v137, v136, v187
	v_sub_f32_e32 v136, v140, v187
	v_sub_f32_e32 v139, v142, v187
	v_sub_f32_e32 v138, v141, v187
	v_sub_f32_e32 v141, v188, v187
	v_sub_f32_e32 v140, v143, v187
	v_sub_f32_e32 v143, v190, v187
	v_sub_f32_e32 v142, v189, v187
	v_pk_mul_f32 v[138:139], v[186:187], v[138:139] op_sel_hi:[0,1]
	v_pk_mul_f32 v[136:137], v[186:187], v[136:137] op_sel_hi:[0,1]
	v_pk_mul_f32 v[142:143], v[186:187], v[142:143] op_sel_hi:[0,1]
	v_pk_mul_f32 v[140:141], v[186:187], v[140:141] op_sel_hi:[0,1]
	v_pk_fma_f32 v[136:137], v[72:73], v[136:137], v[68:69]
	v_pk_fma_f32 v[138:139], v[74:75], v[138:139], v[70:71]
	v_pk_fma_f32 v[140:141], v[64:65], v[140:141], v[76:77]
	v_pk_fma_f32 v[142:143], v[66:67], v[142:143], v[78:79]
	v_pk_fma_f32 v[62:63], v[138:139], s[34:35], v[62:63] op_sel_hi:[1,0,1]
	v_pk_fma_f32 v[60:61], v[136:137], s[34:35], v[60:61] op_sel_hi:[1,0,1]
	v_pk_fma_f32 v[58:59], v[142:143], s[34:35], v[58:59] op_sel_hi:[1,0,1]
	v_pk_fma_f32 v[56:57], v[140:141], s[34:35], v[56:57] op_sel_hi:[1,0,1]
	v_cvt_pk_bf16_f32 v136, v60, v61
	v_cvt_pk_bf16_f32 v137, v62, v63
	v_cvt_pk_bf16_f32 v138, v56, v57
	v_cvt_pk_bf16_f32 v139, v58, v59
	global_store_dwordx4 v[176:177], v[136:139], off offset:256
	global_load_dwordx4 v[244:247], v[192:193], off offset:256
	global_load_dwordx4 v[240:243], v[194:195], off offset:256
	s_nop 0
	s_waitcnt vmcnt(1)
	v_lshlrev_b32_e32 v140, 16, v244
	v_and_b32_e32 v136, 0xffff0000, v244
	v_lshlrev_b32_e32 v141, 16, v245
	v_and_b32_e32 v142, 0xffff0000, v245
	v_lshlrev_b32_e32 v143, 16, v246
	v_and_b32_e32 v176, 0xffff0000, v246
	v_lshlrev_b32_e32 v177, 16, v247
	v_and_b32_e32 v186, 0xffff0000, v247
	v_sub_f32_e32 v137, v136, v197
	v_sub_f32_e32 v136, v140, v197
	v_sub_f32_e32 v139, v142, v197
	v_sub_f32_e32 v138, v141, v197
	v_sub_f32_e32 v141, v176, v197
	v_sub_f32_e32 v140, v143, v197
	v_sub_f32_e32 v143, v186, v197
	v_sub_f32_e32 v142, v177, v197
	v_pk_mul_f32 v[138:139], v[196:197], v[138:139] op_sel_hi:[0,1]
	v_pk_mul_f32 v[136:137], v[196:197], v[136:137] op_sel_hi:[0,1]
	v_pk_mul_f32 v[142:143], v[196:197], v[142:143] op_sel_hi:[0,1]
	v_pk_mul_f32 v[140:141], v[196:197], v[140:141] op_sel_hi:[0,1]
	v_pk_fma_f32 v[136:137], v[72:73], v[136:137], v[68:69]
	v_pk_fma_f32 v[138:139], v[74:75], v[138:139], v[70:71]
	v_pk_fma_f32 v[140:141], v[64:65], v[140:141], v[76:77]
	v_pk_fma_f32 v[142:143], v[66:67], v[142:143], v[78:79]
	v_pk_fma_f32 v[54:55], v[138:139], s[34:35], v[54:55] op_sel_hi:[1,0,1]
	v_pk_fma_f32 v[52:53], v[136:137], s[34:35], v[52:53] op_sel_hi:[1,0,1]
	v_pk_fma_f32 v[50:51], v[142:143], s[34:35], v[50:51] op_sel_hi:[1,0,1]
	v_pk_fma_f32 v[48:49], v[140:141], s[34:35], v[48:49] op_sel_hi:[1,0,1]
	v_cvt_pk_bf16_f32 v136, v52, v53
	v_cvt_pk_bf16_f32 v137, v54, v55
	v_cvt_pk_bf16_f32 v138, v48, v49
	v_cvt_pk_bf16_f32 v139, v50, v51
	global_store_dwordx4 v[192:193], v[136:139], off offset:256
	global_load_dwordx4 v[244:247], v[198:199], off offset:256
	s_nop 0
	s_waitcnt vmcnt(2)
	v_lshlrev_b32_e32 v140, 16, v240
	v_and_b32_e32 v136, 0xffff0000, v240
	v_lshlrev_b32_e32 v141, 16, v241
	v_and_b32_e32 v142, 0xffff0000, v241
	v_lshlrev_b32_e32 v143, 16, v242
	v_and_b32_e32 v176, 0xffff0000, v242
	v_lshlrev_b32_e32 v177, 16, v243
	v_and_b32_e32 v186, 0xffff0000, v243
	v_sub_f32_e32 v137, v136, v201
	v_sub_f32_e32 v136, v140, v201
	v_sub_f32_e32 v139, v142, v201
	v_sub_f32_e32 v138, v141, v201
	v_sub_f32_e32 v141, v176, v201
	v_sub_f32_e32 v140, v143, v201
	v_sub_f32_e32 v143, v186, v201
	v_sub_f32_e32 v142, v177, v201
	v_pk_mul_f32 v[138:139], v[200:201], v[138:139] op_sel_hi:[0,1]
	v_pk_mul_f32 v[136:137], v[200:201], v[136:137] op_sel_hi:[0,1]
	v_pk_mul_f32 v[142:143], v[200:201], v[142:143] op_sel_hi:[0,1]
	v_pk_mul_f32 v[140:141], v[200:201], v[140:141] op_sel_hi:[0,1]
	v_pk_fma_f32 v[136:137], v[72:73], v[136:137], v[68:69]
	v_pk_fma_f32 v[138:139], v[74:75], v[138:139], v[70:71]
	v_pk_fma_f32 v[140:141], v[64:65], v[140:141], v[76:77]
	v_pk_fma_f32 v[142:143], v[66:67], v[142:143], v[78:79]
	v_pk_fma_f32 v[46:47], v[138:139], s[34:35], v[46:47] op_sel_hi:[1,0,1]
	v_pk_fma_f32 v[44:45], v[136:137], s[34:35], v[44:45] op_sel_hi:[1,0,1]
	v_pk_fma_f32 v[42:43], v[142:143], s[34:35], v[42:43] op_sel_hi:[1,0,1]
	v_pk_fma_f32 v[40:41], v[140:141], s[34:35], v[40:41] op_sel_hi:[1,0,1]
	v_cvt_pk_bf16_f32 v136, v44, v45
	v_cvt_pk_bf16_f32 v137, v46, v47
	v_cvt_pk_bf16_f32 v138, v40, v41
	v_cvt_pk_bf16_f32 v139, v42, v43
	global_store_dwordx4 v[194:195], v[136:139], off offset:256
	global_load_dwordx4 v[240:243], v[204:205], off offset:256
	s_nop 0
	s_waitcnt vmcnt(2)
	v_lshlrev_b32_e32 v140, 16, v244
	v_and_b32_e32 v136, 0xffff0000, v244
	v_lshlrev_b32_e32 v141, 16, v245
	v_and_b32_e32 v142, 0xffff0000, v245
	v_lshlrev_b32_e32 v143, 16, v246
	v_and_b32_e32 v176, 0xffff0000, v246
	v_lshlrev_b32_e32 v177, 16, v247
	v_and_b32_e32 v186, 0xffff0000, v247
	v_sub_f32_e32 v137, v136, v207
	v_sub_f32_e32 v136, v140, v207
	v_sub_f32_e32 v139, v142, v207
	v_sub_f32_e32 v138, v141, v207
	v_sub_f32_e32 v141, v176, v207
	v_sub_f32_e32 v140, v143, v207
	v_sub_f32_e32 v143, v186, v207
	v_sub_f32_e32 v142, v177, v207
	v_pk_mul_f32 v[138:139], v[206:207], v[138:139] op_sel_hi:[0,1]
	v_pk_mul_f32 v[136:137], v[206:207], v[136:137] op_sel_hi:[0,1]
	v_pk_mul_f32 v[142:143], v[206:207], v[142:143] op_sel_hi:[0,1]
	v_pk_mul_f32 v[140:141], v[206:207], v[140:141] op_sel_hi:[0,1]
	v_pk_fma_f32 v[136:137], v[72:73], v[136:137], v[68:69]
	v_pk_fma_f32 v[138:139], v[74:75], v[138:139], v[70:71]
	v_pk_fma_f32 v[140:141], v[64:65], v[140:141], v[76:77]
	v_pk_fma_f32 v[142:143], v[66:67], v[142:143], v[78:79]
	v_pk_fma_f32 v[38:39], v[138:139], s[34:35], v[38:39] op_sel_hi:[1,0,1]
	v_pk_fma_f32 v[36:37], v[136:137], s[34:35], v[36:37] op_sel_hi:[1,0,1]
	v_pk_fma_f32 v[34:35], v[142:143], s[34:35], v[34:35] op_sel_hi:[1,0,1]
	v_pk_fma_f32 v[32:33], v[140:141], s[34:35], v[32:33] op_sel_hi:[1,0,1]
	v_cvt_pk_bf16_f32 v136, v36, v37
	v_cvt_pk_bf16_f32 v137, v38, v39
	v_cvt_pk_bf16_f32 v138, v32, v33
	v_cvt_pk_bf16_f32 v139, v34, v35
	global_store_dwordx4 v[198:199], v[136:139], off offset:256
	global_load_dwordx4 v[244:247], v[208:209], off offset:256
	s_nop 0
	s_waitcnt vmcnt(2)
	v_lshlrev_b32_e32 v140, 16, v240
	v_and_b32_e32 v136, 0xffff0000, v240
	v_lshlrev_b32_e32 v141, 16, v241
	v_and_b32_e32 v142, 0xffff0000, v241
	v_lshlrev_b32_e32 v143, 16, v242
	v_and_b32_e32 v176, 0xffff0000, v242
	v_lshlrev_b32_e32 v177, 16, v243
	v_and_b32_e32 v186, 0xffff0000, v243
	v_sub_f32_e32 v137, v136, v211
	v_sub_f32_e32 v136, v140, v211
	v_sub_f32_e32 v139, v142, v211
	v_sub_f32_e32 v138, v141, v211
	v_sub_f32_e32 v141, v176, v211
	v_sub_f32_e32 v140, v143, v211
	v_sub_f32_e32 v143, v186, v211
	v_sub_f32_e32 v142, v177, v211
	v_pk_mul_f32 v[138:139], v[210:211], v[138:139] op_sel_hi:[0,1]
	v_pk_mul_f32 v[136:137], v[210:211], v[136:137] op_sel_hi:[0,1]
	v_pk_mul_f32 v[142:143], v[210:211], v[142:143] op_sel_hi:[0,1]
	v_pk_mul_f32 v[140:141], v[210:211], v[140:141] op_sel_hi:[0,1]
	v_pk_fma_f32 v[136:137], v[72:73], v[136:137], v[68:69]
	v_pk_fma_f32 v[138:139], v[74:75], v[138:139], v[70:71]
	v_pk_fma_f32 v[140:141], v[64:65], v[140:141], v[76:77]
	v_pk_fma_f32 v[142:143], v[66:67], v[142:143], v[78:79]
	v_pk_fma_f32 v[30:31], v[138:139], s[34:35], v[30:31] op_sel_hi:[1,0,1]
	v_pk_fma_f32 v[28:29], v[136:137], s[34:35], v[28:29] op_sel_hi:[1,0,1]
	v_pk_fma_f32 v[26:27], v[142:143], s[34:35], v[26:27] op_sel_hi:[1,0,1]
	v_pk_fma_f32 v[24:25], v[140:141], s[34:35], v[24:25] op_sel_hi:[1,0,1]
	v_cvt_pk_bf16_f32 v136, v28, v29
	v_cvt_pk_bf16_f32 v137, v30, v31
	v_cvt_pk_bf16_f32 v138, v24, v25
	v_cvt_pk_bf16_f32 v139, v26, v27
	global_store_dwordx4 v[204:205], v[136:139], off offset:256
	global_load_dwordx4 v[240:243], v[214:215], off offset:256
	s_nop 0
	s_waitcnt vmcnt(2)
	v_lshlrev_b32_e32 v140, 16, v244
	v_and_b32_e32 v136, 0xffff0000, v244
	v_lshlrev_b32_e32 v141, 16, v245
	v_and_b32_e32 v142, 0xffff0000, v245
	v_lshlrev_b32_e32 v143, 16, v246
	v_and_b32_e32 v176, 0xffff0000, v246
	v_lshlrev_b32_e32 v177, 16, v247
	v_and_b32_e32 v186, 0xffff0000, v247
	v_sub_f32_e32 v137, v136, v217
	v_sub_f32_e32 v136, v140, v217
	v_sub_f32_e32 v139, v142, v217
	v_sub_f32_e32 v138, v141, v217
	v_sub_f32_e32 v141, v176, v217
	v_sub_f32_e32 v140, v143, v217
	v_sub_f32_e32 v143, v186, v217
	v_sub_f32_e32 v142, v177, v217
	v_pk_mul_f32 v[138:139], v[216:217], v[138:139] op_sel_hi:[0,1]
	v_pk_mul_f32 v[136:137], v[216:217], v[136:137] op_sel_hi:[0,1]
	v_pk_mul_f32 v[142:143], v[216:217], v[142:143] op_sel_hi:[0,1]
	v_pk_mul_f32 v[140:141], v[216:217], v[140:141] op_sel_hi:[0,1]
	v_pk_fma_f32 v[136:137], v[72:73], v[136:137], v[68:69]
	v_pk_fma_f32 v[138:139], v[74:75], v[138:139], v[70:71]
	v_pk_fma_f32 v[140:141], v[64:65], v[140:141], v[76:77]
	v_pk_fma_f32 v[142:143], v[66:67], v[142:143], v[78:79]
	v_pk_fma_f32 v[22:23], v[138:139], s[34:35], v[22:23] op_sel_hi:[1,0,1]
	v_pk_fma_f32 v[20:21], v[136:137], s[34:35], v[20:21] op_sel_hi:[1,0,1]
	v_pk_fma_f32 v[18:19], v[142:143], s[34:35], v[18:19] op_sel_hi:[1,0,1]
	v_pk_fma_f32 v[16:17], v[140:141], s[34:35], v[16:17] op_sel_hi:[1,0,1]
	v_cvt_pk_bf16_f32 v136, v20, v21
	v_cvt_pk_bf16_f32 v137, v22, v23
	v_cvt_pk_bf16_f32 v138, v16, v17
	v_cvt_pk_bf16_f32 v139, v18, v19
	global_store_dwordx4 v[208:209], v[136:139], off offset:256
	s_nop 0
	s_waitcnt vmcnt(1)
	v_lshlrev_b32_e32 v140, 16, v240
	v_and_b32_e32 v136, 0xffff0000, v240
	v_lshlrev_b32_e32 v141, 16, v241
	v_and_b32_e32 v142, 0xffff0000, v241
	v_lshlrev_b32_e32 v143, 16, v242
	v_and_b32_e32 v176, 0xffff0000, v242
	v_lshlrev_b32_e32 v177, 16, v243
	v_and_b32_e32 v186, 0xffff0000, v243
	v_sub_f32_e32 v137, v136, v219
	v_sub_f32_e32 v136, v140, v219
	v_sub_f32_e32 v139, v142, v219
	v_sub_f32_e32 v138, v141, v219
	v_sub_f32_e32 v141, v176, v219
	v_sub_f32_e32 v140, v143, v219
	v_sub_f32_e32 v143, v186, v219
	v_sub_f32_e32 v142, v177, v219
	v_pk_mul_f32 v[138:139], v[218:219], v[138:139] op_sel_hi:[0,1]
	v_pk_mul_f32 v[136:137], v[218:219], v[136:137] op_sel_hi:[0,1]
	v_pk_mul_f32 v[142:143], v[218:219], v[142:143] op_sel_hi:[0,1]
	v_pk_mul_f32 v[140:141], v[218:219], v[140:141] op_sel_hi:[0,1]
	v_pk_fma_f32 v[136:137], v[72:73], v[136:137], v[68:69]
	v_pk_fma_f32 v[138:139], v[74:75], v[138:139], v[70:71]
	v_pk_fma_f32 v[140:141], v[64:65], v[140:141], v[76:77]
	v_pk_fma_f32 v[142:143], v[66:67], v[142:143], v[78:79]
	v_pk_fma_f32 v[14:15], v[138:139], s[34:35], v[14:15] op_sel_hi:[1,0,1]
	v_pk_fma_f32 v[12:13], v[136:137], s[34:35], v[12:13] op_sel_hi:[1,0,1]
	v_pk_fma_f32 v[10:11], v[142:143], s[34:35], v[10:11] op_sel_hi:[1,0,1]
	v_pk_fma_f32 v[8:9], v[140:141], s[34:35], v[8:9] op_sel_hi:[1,0,1]
	v_cvt_pk_bf16_f32 v136, v12, v13
	v_cvt_pk_bf16_f32 v137, v14, v15
	v_cvt_pk_bf16_f32 v138, v8, v9
	v_cvt_pk_bf16_f32 v139, v10, v11
	global_store_dwordx4 v[214:215], v[136:139], off offset:256
	global_load_dwordx4 v[136:139], v[212:213], off offset:256
	v_add_f32_e32 v140, v124, v125
	v_add_f32_e32 v141, v126, v127
	v_add_f32_e32 v142, v120, v121
	v_add_f32_e32 v143, v122, v123
	v_mul_f32_e32 v125, v125, v125
	v_mul_f32_e32 v127, v127, v127
	v_mul_f32_e32 v121, v121, v121
	v_mul_f32_e32 v123, v123, v123
	v_fmac_f32_e32 v125, v124, v124
	v_fmac_f32_e32 v127, v126, v126
	v_fmac_f32_e32 v121, v120, v120
	v_fmac_f32_e32 v123, v122, v122
	v_add_f32_e32 v122, v125, v127
	v_add_f32_e32 v121, v121, v123
	v_add_f32_e32 v121, v122, v121
	v_add_f32_e32 v122, v60, v61
	v_add_f32_e32 v123, v62, v63
	v_add_f32_e32 v124, v56, v57
	v_add_f32_e32 v125, v58, v59
	v_mul_f32_e32 v61, v61, v61
	v_mul_f32_e32 v63, v63, v63
	v_mul_f32_e32 v57, v57, v57
	v_mul_f32_e32 v59, v59, v59
	v_add_f32_e32 v140, v140, v141
	v_add_f32_e32 v141, v142, v143
	v_fmac_f32_e32 v61, v60, v60
	v_fmac_f32_e32 v63, v62, v62
	v_fmac_f32_e32 v57, v56, v56
	v_fmac_f32_e32 v59, v58, v58
	v_add_f32_e32 v120, v140, v141
	v_add_f32_e32 v122, v122, v123
	v_add_f32_e32 v123, v124, v125
	v_add_f32_e32 v58, v61, v63
	v_add_f32_e32 v57, v57, v59
	v_add_f32_e32 v120, 0, v120
	v_add_f32_e32 v56, v122, v123
	v_add_f32_e32 v57, v58, v57
	v_add_f32_e32 v56, v120, v56
	v_add_f32_e32 v59, v121, v57
	ds_bpermute_b32 v58, v222, v56
	ds_bpermute_b32 v60, v222, v59
	s_waitcnt lgkmcnt(0)
	v_add_f32_e32 v56, v56, v58
	v_add_f32_e32 v58, v59, v60
	ds_bpermute_b32 v57, v221, v56
	s_waitcnt vmcnt(0)
	v_lshlrev_b32_e32 v59, 16, v136
	v_and_b32_e32 v60, 0xffff0000, v136
	v_lshlrev_b32_e32 v62, 16, v137
	v_and_b32_e32 v63, 0xffff0000, v137
	v_lshlrev_b32_e32 v120, 16, v138
	v_and_b32_e32 v121, 0xffff0000, v138
	v_lshlrev_b32_e32 v122, 16, v139
	v_and_b32_e32 v123, 0xffff0000, v139
	v_sub_f32_e32 v61, v60, v203
	v_sub_f32_e32 v60, v59, v203
	v_sub_f32_e32 v63, v63, v203
	v_sub_f32_e32 v62, v62, v203
	v_sub_f32_e32 v121, v121, v203
	v_sub_f32_e32 v120, v120, v203
	v_sub_f32_e32 v123, v123, v203
	v_sub_f32_e32 v122, v122, v203
	v_pk_mul_f32 v[62:63], v[202:203], v[62:63] op_sel_hi:[0,1]
	v_pk_mul_f32 v[60:61], v[202:203], v[60:61] op_sel_hi:[0,1]
	v_pk_mul_f32 v[122:123], v[202:203], v[122:123] op_sel_hi:[0,1]
	v_pk_mul_f32 v[120:121], v[202:203], v[120:121] op_sel_hi:[0,1]
	v_pk_fma_f32 v[60:61], v[72:73], v[60:61], v[68:69]
	v_pk_fma_f32 v[62:63], v[74:75], v[62:63], v[70:71]
	v_pk_fma_f32 v[64:65], v[64:65], v[120:121], v[76:77]
	v_pk_fma_f32 v[66:67], v[66:67], v[122:123], v[78:79]
	v_pk_fma_f32 v[6:7], v[62:63], s[34:35], v[6:7] op_sel_hi:[1,0,1]
	v_pk_fma_f32 v[4:5], v[60:61], s[34:35], v[4:5] op_sel_hi:[1,0,1]
	v_pk_fma_f32 v[2:3], v[66:67], s[34:35], v[2:3] op_sel_hi:[1,0,1]
	v_pk_fma_f32 v[0:1], v[64:65], s[34:35], v[0:1] op_sel_hi:[1,0,1]
	v_cvt_pk_bf16_f32 v60, v4, v5
	v_cvt_pk_bf16_f32 v61, v6, v7
	v_cvt_pk_bf16_f32 v62, v0, v1
	v_cvt_pk_bf16_f32 v63, v2, v3
	ds_bpermute_b32 v59, v221, v58
	global_store_dwordx4 v[212:213], v[60:63], off offset:256
	s_and_saveexec_b64 s[0:1], s[6:7]
	s_cbranch_execz .LBB0_1297
	s_waitcnt lgkmcnt(0)
	v_add_f32_e32 v58, v58, v59
	v_add_f32_e32 v59, v56, v57
	v_lshl_add_u64 v[56:57], s[18:19], 0, v[164:165]
	global_atomic_add_f32 v[56:57], v59, off
	global_atomic_add_f32 v[56:57], v58, off offset:4

.LBB0_1475:
	v_lshl_add_u32 v128, s77, 8, v218
	v_ashrrev_i32_e32 v129, 31, v128
	v_lshlrev_b64 v[164:165], 3, v[128:129]
	v_lshl_add_u64 v[130:131], s[18:19], 0, v[164:165]
	v_lshl_or_b32 v186, s76, 8, v223
	global_load_dwordx2 v[188:189], v[130:131], off
	v_ashrrev_i32_e32 v187, 31, v186
	v_lshlrev_b64 v[130:131], 12, v[128:129]
	v_lshl_add_u64 v[130:131], s[16:17], 0, v[130:131]
	v_lshlrev_b64 v[178:179], 1, v[186:187]
	v_lshl_add_u64 v[176:177], v[130:131], 0, v[178:179]
	global_load_dwordx4 v[190:193], v[176:177], off
	v_or_b32_e32 v194, 16, v128
	v_or_b32_e32 v216, 32, v128
	v_or_b32_e32 v196, 48, v128
	v_add_u32_e32 v202, 0x80, v128
	v_add_u32_e32 v206, 0x90, v128
	v_add_u32_e32 v184, 0xa0, v128
	v_add_u32_e32 v180, 0xb0, v128
	v_lshlrev_b64 v[128:129], 2, v[186:187]
	v_lshl_add_u64 v[132:133], s[14:15], 0, v[128:129]
	v_lshl_add_u64 v[140:141], s[20:21], 0, v[128:129]
	global_load_dwordx4 v[128:131], v[132:133], off offset:16
	global_load_dwordx4 v[136:139], v[132:133], off
	s_nop 0
	global_load_dwordx4 v[132:135], v[140:141], off offset:16
	s_nop 0
	global_load_dwordx4 v[140:143], v[140:141], off
	v_ashrrev_i32_e32 v195, 31, v194
	v_ashrrev_i32_e32 v217, 31, v216
	v_ashrrev_i32_e32 v197, 31, v196
	v_ashrrev_i32_e32 v203, 31, v202
	v_ashrrev_i32_e32 v207, 31, v206
	v_ashrrev_i32_e32 v185, 31, v184
	v_ashrrev_i32_e32 v181, 31, v180
	v_lshlrev_b64 v[174:175], 3, v[194:195]
	v_lshlrev_b64 v[172:173], 3, v[216:217]
	v_lshlrev_b64 v[170:171], 3, v[196:197]
	v_lshlrev_b64 v[168:169], 3, v[202:203]
	v_lshlrev_b64 v[166:167], 3, v[206:207]
	v_lshlrev_b64 v[162:163], 3, v[184:185]
	v_lshlrev_b64 v[160:161], 3, v[180:181]
	v_lshl_add_u64 v[182:183], s[18:19], 0, v[174:175]
	v_lshl_add_u64 v[198:199], s[18:19], 0, v[172:173]
	v_lshl_add_u64 v[200:201], s[18:19], 0, v[170:171]
	v_lshl_add_u64 v[208:209], s[18:19], 0, v[168:169]
	v_lshl_add_u64 v[210:211], s[18:19], 0, v[166:167]
	v_lshl_add_u64 v[212:213], s[18:19], 0, v[162:163]
	v_lshl_add_u64 v[214:215], s[18:19], 0, v[160:161]
	global_load_dwordx2 v[228:229], v[182:183], off
	s_nop 0
	global_load_dwordx2 v[198:199], v[198:199], off
	s_nop 0
	global_load_dwordx2 v[204:205], v[200:201], off
	s_nop 0
	global_load_dwordx2 v[208:209], v[208:209], off
	s_nop 0
	global_load_dwordx2 v[210:211], v[210:211], off
	s_nop 0
	global_load_dwordx2 v[182:183], v[212:213], off
	global_load_dwordx2 v[200:201], v[214:215], off
	v_lshlrev_b64 v[196:197], 12, v[196:197]
	v_lshl_add_u64 v[196:197], s[16:17], 0, v[196:197]
	v_lshl_add_u64 v[196:197], v[196:197], 0, v[178:179]
	v_lshlrev_b64 v[202:203], 12, v[202:203]
	v_lshl_add_u64 v[202:203], s[16:17], 0, v[202:203]
	v_lshl_add_u64 v[202:203], v[202:203], 0, v[178:179]
	v_lshlrev_b64 v[206:207], 12, v[206:207]
	v_lshl_add_u64 v[206:207], s[16:17], 0, v[206:207]
	v_lshl_add_u64 v[206:207], v[206:207], 0, v[178:179]
	v_lshlrev_b64 v[184:185], 12, v[184:185]
	v_lshl_add_u64 v[184:185], s[16:17], 0, v[184:185]
	v_lshlrev_b64 v[180:181], 12, v[180:181]
	v_lshl_add_u64 v[180:181], s[16:17], 0, v[180:181]
	s_waitcnt vmcnt(0)
	v_pk_mul_f32 v[188:189], v[188:189], s[30:31] op_sel:[1,0] op_sel_hi:[0,0]
	v_fma_f32 v187, -v189, v189, v188
	v_max_f32_e32 v187, 0, v187
	v_add_f32_e32 v187, 0x3727c5ac, v187
	v_cmp_gt_f32_e32 vcc, s61, v187
	v_lshlrev_b32_e32 v188, 16, v190
	v_and_b32_e32 v190, 0xffff0000, v190
	v_lshlrev_b32_e32 v212, 16, v191
	v_and_b32_e32 v213, 0xffff0000, v191
	v_sub_f32_e32 v191, v190, v189
	v_sub_f32_e32 v190, v188, v189
	v_mul_f32_e32 v188, 0x4f800000, v187
	v_cndmask_b32_e32 v187, v187, v188, vcc
	v_sqrt_f32_e32 v188, v187
	v_lshlrev_b32_e32 v214, 16, v192
	v_and_b32_e32 v215, 0xffff0000, v192
	v_and_b32_e32 v231, 0xffff0000, v193
	v_sub_f32_e32 v192, v212, v189
	v_sub_f32_e32 v212, v214, v189
	v_add_u32_e32 v214, -1, v188
	v_lshlrev_b32_e32 v230, 16, v193
	v_sub_f32_e32 v193, v213, v189
	v_sub_f32_e32 v213, v215, v189
	v_sub_f32_e32 v215, v231, v189
	v_add_u32_e32 v231, 1, v188
	v_fma_f32 v232, -v214, v188, v187
	v_fma_f32 v233, -v231, v188, v187
	v_cmp_ge_f32_e64 s[0:1], 0, v232
	v_pk_mul_f32 v[198:199], v[198:199], s[30:31] op_sel:[1,0] op_sel_hi:[0,0]
	s_nop 0
	v_cndmask_b32_e64 v188, v188, v214, s[0:1]
	v_cmp_lt_f32_e64 s[0:1], 0, v233
	v_pk_mul_f32 v[204:205], v[204:205], s[30:31] op_sel:[1,0] op_sel_hi:[0,0]
	v_pk_mul_f32 v[208:209], v[208:209], s[30:31] op_sel:[1,0] op_sel_hi:[0,0]
	v_cndmask_b32_e64 v188, v188, v231, s[0:1]
	v_mul_f32_e32 v214, 0x37800000, v188
	v_cndmask_b32_e32 v188, v188, v214, vcc
	v_cmp_class_f32_e32 vcc, v187, v227
	v_sub_f32_e32 v214, v230, v189
	v_pk_mul_f32 v[200:201], v[200:201], s[30:31] op_sel:[1,0] op_sel_hi:[0,0]
	v_cndmask_b32_e32 v187, v188, v187, vcc
	v_div_scale_f32 v188, s[0:1], v187, v187, 1.0
	v_rcp_f32_e32 v231, v188
	v_div_scale_f32 v230, vcc, 1.0, v187, 1.0
	v_fma_f32 v232, -v188, v231, 1.0
	v_fmac_f32_e32 v231, v232, v231
	v_mul_f32_e32 v232, v230, v231
	v_fma_f32 v233, -v188, v232, v230
	v_fmac_f32_e32 v232, v233, v231
	v_fma_f32 v188, -v188, v232, v230
	v_div_fmas_f32 v188, v188, v231, v232
	v_div_fixup_f32 v188, v188, v187, 1.0
	v_pk_mul_f32 v[192:193], v[188:189], v[192:193] op_sel_hi:[0,1]
	v_pk_mul_f32 v[190:191], v[188:189], v[190:191] op_sel_hi:[0,1]
	v_pk_mul_f32 v[214:215], v[188:189], v[214:215] op_sel_hi:[0,1]
	v_pk_mul_f32 v[212:213], v[188:189], v[212:213] op_sel_hi:[0,1]
	v_pk_fma_f32 v[190:191], v[136:137], v[190:191], v[140:141]
	v_pk_fma_f32 v[192:193], v[138:139], v[192:193], v[142:143]
	v_pk_fma_f32 v[212:213], v[128:129], v[212:213], v[132:133]
	v_pk_fma_f32 v[214:215], v[130:131], v[214:215], v[134:135]
	v_pk_fma_f32 v[126:127], v[192:193], s[34:35], v[126:127] op_sel_hi:[1,0,1]
	v_pk_fma_f32 v[124:125], v[190:191], s[34:35], v[124:125] op_sel_hi:[1,0,1]
	v_pk_fma_f32 v[122:123], v[214:215], s[34:35], v[122:123] op_sel_hi:[1,0,1]
	v_pk_fma_f32 v[120:121], v[212:213], s[34:35], v[120:121] op_sel_hi:[1,0,1]
	v_cvt_pk_bf16_f32 v190, v124, v125
	v_cvt_pk_bf16_f32 v191, v126, v127
	v_cvt_pk_bf16_f32 v192, v120, v121
	v_cvt_pk_bf16_f32 v193, v122, v123
	global_store_dwordx4 v[176:177], v[190:193], off
	s_nop 1
	v_lshlrev_b64 v[190:191], 12, v[194:195]
	v_lshl_add_u64 v[190:191], s[16:17], 0, v[190:191]
	v_lshl_add_u64 v[190:191], v[190:191], 0, v[178:179]
	global_load_dwordx4 v[212:215], v[190:191], off
	v_pk_mul_f32 v[194:195], v[228:229], s[30:31] op_sel:[1,0] op_sel_hi:[0,0]
	v_fma_f32 v187, -v195, v195, v194
	v_max_f32_e32 v187, 0, v187
	v_add_f32_e32 v187, 0x3727c5ac, v187
	v_mul_f32_e32 v192, 0x4f800000, v187
	v_cmp_gt_f32_e32 vcc, s61, v187
	s_waitcnt vmcnt(0)
	v_lshlrev_b32_e32 v230, 16, v215
	v_cndmask_b32_e32 v187, v187, v192, vcc
	v_sqrt_f32_e32 v194, v187
	v_lshlrev_b64 v[192:193], 12, v[216:217]
	v_and_b32_e32 v231, 0xffff0000, v215
	v_lshl_add_u64 v[192:193], s[16:17], 0, v[192:193]
	v_add_u32_e32 v216, -1, v194
	v_add_u32_e32 v217, 1, v194
	v_fma_f32 v228, -v216, v194, v187
	v_fma_f32 v229, -v217, v194, v187
	v_cmp_ge_f32_e64 s[0:1], 0, v228
	v_lshl_add_u64 v[192:193], v[192:193], 0, v[178:179]
	s_nop 0
	v_cndmask_b32_e64 v194, v194, v216, s[0:1]
	v_cmp_lt_f32_e64 s[0:1], 0, v229
	s_nop 1
	v_cndmask_b32_e64 v194, v194, v217, s[0:1]
	v_mul_f32_e32 v216, 0x37800000, v194
	v_cndmask_b32_e32 v194, v194, v216, vcc
	v_cmp_class_f32_e32 vcc, v187, v227
	s_nop 1
	v_cndmask_b32_e32 v187, v194, v187, vcc
	v_div_scale_f32 v194, s[0:1], v187, v187, 1.0
	v_rcp_f32_e32 v216, v194
	v_div_scale_f32 v217, vcc, 1.0, v187, 1.0
	v_fma_f32 v228, -v194, v216, 1.0
	v_fmac_f32_e32 v216, v228, v216
	v_mul_f32_e32 v228, v217, v216
	v_fma_f32 v229, -v194, v228, v217
	v_fmac_f32_e32 v228, v229, v216
	v_fma_f32 v194, -v194, v228, v217
	v_div_fmas_f32 v194, v194, v216, v228
	v_div_fixup_f32 v194, v194, v187, 1.0
	v_lshlrev_b32_e32 v187, 16, v212
	v_and_b32_e32 v212, 0xffff0000, v212
	v_lshlrev_b32_e32 v216, 16, v213
	v_and_b32_e32 v217, 0xffff0000, v213
	v_lshlrev_b32_e32 v228, 16, v214
	v_and_b32_e32 v229, 0xffff0000, v214
	v_sub_f32_e32 v213, v212, v195
	v_sub_f32_e32 v212, v187, v195
	v_sub_f32_e32 v215, v217, v195
	v_sub_f32_e32 v214, v216, v195
	v_sub_f32_e32 v217, v229, v195
	v_sub_f32_e32 v216, v228, v195
	v_sub_f32_e32 v229, v231, v195
	v_sub_f32_e32 v228, v230, v195
	v_pk_mul_f32 v[214:215], v[194:195], v[214:215] op_sel_hi:[0,1]
	v_pk_mul_f32 v[212:213], v[194:195], v[212:213] op_sel_hi:[0,1]
	v_pk_mul_f32 v[228:229], v[194:195], v[228:229] op_sel_hi:[0,1]
	v_pk_mul_f32 v[216:217], v[194:195], v[216:217] op_sel_hi:[0,1]
	v_pk_fma_f32 v[212:213], v[136:137], v[212:213], v[140:141]
	v_pk_fma_f32 v[214:215], v[138:139], v[214:215], v[142:143]
	v_pk_fma_f32 v[216:217], v[128:129], v[216:217], v[132:133]
	v_pk_fma_f32 v[228:229], v[130:131], v[228:229], v[134:135]
	v_pk_fma_f32 v[118:119], v[214:215], s[34:35], v[118:119] op_sel_hi:[1,0,1]
	v_pk_fma_f32 v[116:117], v[212:213], s[34:35], v[116:117] op_sel_hi:[1,0,1]
	v_pk_fma_f32 v[114:115], v[228:229], s[34:35], v[114:115] op_sel_hi:[1,0,1]
	v_pk_fma_f32 v[112:113], v[216:217], s[34:35], v[112:113] op_sel_hi:[1,0,1]
	v_cvt_pk_bf16_f32 v212, v116, v117
	v_cvt_pk_bf16_f32 v213, v118, v119
	v_cvt_pk_bf16_f32 v214, v112, v113
	v_cvt_pk_bf16_f32 v215, v114, v115
	global_store_dwordx4 v[190:191], v[212:215], off
	global_load_dwordx4 v[212:215], v[192:193], off
	v_fma_f32 v187, -v199, v199, v198
	v_max_f32_e32 v187, 0, v187
	v_add_f32_e32 v187, 0x3727c5ac, v187
	v_mul_f32_e32 v198, 0x4f800000, v187
	v_cmp_gt_f32_e32 vcc, s61, v187
	s_waitcnt vmcnt(0)
	v_lshlrev_b32_e32 v230, 16, v215
	v_cndmask_b32_e32 v187, v187, v198, vcc
	v_sqrt_f32_e32 v198, v187
	v_and_b32_e32 v231, 0xffff0000, v215
	v_add_u32_e32 v216, -1, v198
	v_add_u32_e32 v217, 1, v198
	v_fma_f32 v228, -v216, v198, v187
	v_fma_f32 v229, -v217, v198, v187
	v_cmp_ge_f32_e64 s[0:1], 0, v228
	s_nop 1
	v_cndmask_b32_e64 v198, v198, v216, s[0:1]
	v_cmp_lt_f32_e64 s[0:1], 0, v229
	s_nop 1
	v_cndmask_b32_e64 v198, v198, v217, s[0:1]
	v_mul_f32_e32 v216, 0x37800000, v198
	v_cndmask_b32_e32 v198, v198, v216, vcc
	v_cmp_class_f32_e32 vcc, v187, v227
	s_nop 1
	v_cndmask_b32_e32 v187, v198, v187, vcc
	v_div_scale_f32 v198, s[0:1], v187, v187, 1.0
	v_rcp_f32_e32 v216, v198
	v_div_scale_f32 v217, vcc, 1.0, v187, 1.0
	v_fma_f32 v228, -v198, v216, 1.0
	v_fmac_f32_e32 v216, v228, v216
	v_mul_f32_e32 v228, v217, v216
	v_fma_f32 v229, -v198, v228, v217
	v_fmac_f32_e32 v228, v229, v216
	v_fma_f32 v198, -v198, v228, v217
	v_div_fmas_f32 v198, v198, v216, v228
	v_div_fixup_f32 v198, v198, v187, 1.0
	v_lshlrev_b32_e32 v187, 16, v212
	v_and_b32_e32 v212, 0xffff0000, v212
	v_lshlrev_b32_e32 v216, 16, v213
	v_and_b32_e32 v217, 0xffff0000, v213
	v_lshlrev_b32_e32 v228, 16, v214
	v_and_b32_e32 v229, 0xffff0000, v214
	v_sub_f32_e32 v213, v212, v199
	v_sub_f32_e32 v212, v187, v199
	v_sub_f32_e32 v215, v217, v199
	v_sub_f32_e32 v214, v216, v199
	v_sub_f32_e32 v217, v229, v199
	v_sub_f32_e32 v216, v228, v199
	v_sub_f32_e32 v229, v231, v199
	v_sub_f32_e32 v228, v230, v199
	v_pk_mul_f32 v[214:215], v[198:199], v[214:215] op_sel_hi:[0,1]
	v_pk_mul_f32 v[212:213], v[198:199], v[212:213] op_sel_hi:[0,1]
	v_pk_mul_f32 v[228:229], v[198:199], v[228:229] op_sel_hi:[0,1]
	v_pk_mul_f32 v[216:217], v[198:199], v[216:217] op_sel_hi:[0,1]
	v_pk_fma_f32 v[212:213], v[136:137], v[212:213], v[140:141]
	v_pk_fma_f32 v[214:215], v[138:139], v[214:215], v[142:143]
	v_pk_fma_f32 v[216:217], v[128:129], v[216:217], v[132:133]
	v_pk_fma_f32 v[228:229], v[130:131], v[228:229], v[134:135]
	v_pk_fma_f32 v[110:111], v[214:215], s[34:35], v[110:111] op_sel_hi:[1,0,1]
	v_pk_fma_f32 v[108:109], v[212:213], s[34:35], v[108:109] op_sel_hi:[1,0,1]
	v_pk_fma_f32 v[106:107], v[228:229], s[34:35], v[106:107] op_sel_hi:[1,0,1]
	v_pk_fma_f32 v[104:105], v[216:217], s[34:35], v[104:105] op_sel_hi:[1,0,1]
	v_cvt_pk_bf16_f32 v212, v108, v109
	v_cvt_pk_bf16_f32 v213, v110, v111
	v_cvt_pk_bf16_f32 v214, v104, v105
	v_cvt_pk_bf16_f32 v215, v106, v107
	global_store_dwordx4 v[192:193], v[212:215], off
	global_load_dwordx4 v[212:215], v[196:197], off
	v_fma_f32 v187, -v205, v205, v204
	v_max_f32_e32 v187, 0, v187
	v_add_f32_e32 v187, 0x3727c5ac, v187
	v_mul_f32_e32 v204, 0x4f800000, v187
	v_cmp_gt_f32_e32 vcc, s61, v187
	s_waitcnt vmcnt(0)
	v_lshlrev_b32_e32 v230, 16, v215
	v_cndmask_b32_e32 v187, v187, v204, vcc
	v_sqrt_f32_e32 v204, v187
	v_and_b32_e32 v231, 0xffff0000, v215
	v_add_u32_e32 v216, -1, v204
	v_add_u32_e32 v217, 1, v204
	v_fma_f32 v228, -v216, v204, v187
	v_fma_f32 v229, -v217, v204, v187
	v_cmp_ge_f32_e64 s[0:1], 0, v228
	s_nop 1
	v_cndmask_b32_e64 v204, v204, v216, s[0:1]
	v_cmp_lt_f32_e64 s[0:1], 0, v229
	s_nop 1
	v_cndmask_b32_e64 v204, v204, v217, s[0:1]
	v_mul_f32_e32 v216, 0x37800000, v204
	v_cndmask_b32_e32 v204, v204, v216, vcc
	v_cmp_class_f32_e32 vcc, v187, v227
	s_nop 1
	v_cndmask_b32_e32 v187, v204, v187, vcc
	v_div_scale_f32 v204, s[0:1], v187, v187, 1.0
	v_rcp_f32_e32 v216, v204
	v_div_scale_f32 v217, vcc, 1.0, v187, 1.0
	v_fma_f32 v228, -v204, v216, 1.0
	v_fmac_f32_e32 v216, v228, v216
	v_mul_f32_e32 v228, v217, v216
	v_fma_f32 v229, -v204, v228, v217
	v_fmac_f32_e32 v228, v229, v216
	v_fma_f32 v204, -v204, v228, v217
	v_div_fmas_f32 v204, v204, v216, v228
	v_div_fixup_f32 v204, v204, v187, 1.0
	v_lshlrev_b32_e32 v187, 16, v212
	v_and_b32_e32 v212, 0xffff0000, v212
	v_lshlrev_b32_e32 v216, 16, v213
	v_and_b32_e32 v217, 0xffff0000, v213
	v_lshlrev_b32_e32 v228, 16, v214
	v_and_b32_e32 v229, 0xffff0000, v214
	v_sub_f32_e32 v213, v212, v205
	v_sub_f32_e32 v212, v187, v205
	v_sub_f32_e32 v215, v217, v205
	v_sub_f32_e32 v214, v216, v205
	v_sub_f32_e32 v217, v229, v205
	v_sub_f32_e32 v216, v228, v205
	v_sub_f32_e32 v229, v231, v205
	v_sub_f32_e32 v228, v230, v205
	v_pk_mul_f32 v[214:215], v[204:205], v[214:215] op_sel_hi:[0,1]
	v_pk_mul_f32 v[212:213], v[204:205], v[212:213] op_sel_hi:[0,1]
	v_pk_mul_f32 v[228:229], v[204:205], v[228:229] op_sel_hi:[0,1]
	v_pk_mul_f32 v[216:217], v[204:205], v[216:217] op_sel_hi:[0,1]
	v_pk_fma_f32 v[212:213], v[136:137], v[212:213], v[140:141]
	v_pk_fma_f32 v[214:215], v[138:139], v[214:215], v[142:143]
	v_pk_fma_f32 v[216:217], v[128:129], v[216:217], v[132:133]
	v_pk_fma_f32 v[228:229], v[130:131], v[228:229], v[134:135]
	v_pk_fma_f32 v[102:103], v[214:215], s[34:35], v[102:103] op_sel_hi:[1,0,1]
	v_pk_fma_f32 v[100:101], v[212:213], s[34:35], v[100:101] op_sel_hi:[1,0,1]
	v_pk_fma_f32 v[98:99], v[228:229], s[34:35], v[98:99] op_sel_hi:[1,0,1]
	v_pk_fma_f32 v[96:97], v[216:217], s[34:35], v[96:97] op_sel_hi:[1,0,1]
	v_cvt_pk_bf16_f32 v212, v100, v101
	v_cvt_pk_bf16_f32 v213, v102, v103
	v_cvt_pk_bf16_f32 v214, v96, v97
	v_cvt_pk_bf16_f32 v215, v98, v99
	global_store_dwordx4 v[196:197], v[212:215], off
	global_load_dwordx4 v[212:215], v[202:203], off
	v_fma_f32 v187, -v209, v209, v208
	v_max_f32_e32 v187, 0, v187
	v_add_f32_e32 v187, 0x3727c5ac, v187
	v_mul_f32_e32 v208, 0x4f800000, v187
	v_cmp_gt_f32_e32 vcc, s61, v187
	s_waitcnt vmcnt(0)
	v_lshlrev_b32_e32 v230, 16, v215
	v_cndmask_b32_e32 v187, v187, v208, vcc
	v_sqrt_f32_e32 v208, v187
	v_and_b32_e32 v231, 0xffff0000, v215
	v_add_u32_e32 v216, -1, v208
	v_add_u32_e32 v217, 1, v208
	v_fma_f32 v228, -v216, v208, v187
	v_fma_f32 v229, -v217, v208, v187
	v_cmp_ge_f32_e64 s[0:1], 0, v228
	s_nop 1
	v_cndmask_b32_e64 v208, v208, v216, s[0:1]
	v_cmp_lt_f32_e64 s[0:1], 0, v229
	s_nop 1
	v_cndmask_b32_e64 v208, v208, v217, s[0:1]
	v_mul_f32_e32 v216, 0x37800000, v208
	v_cndmask_b32_e32 v208, v208, v216, vcc
	v_cmp_class_f32_e32 vcc, v187, v227
	s_nop 1
	v_cndmask_b32_e32 v187, v208, v187, vcc
	v_div_scale_f32 v208, s[0:1], v187, v187, 1.0
	v_rcp_f32_e32 v216, v208
	v_div_scale_f32 v217, vcc, 1.0, v187, 1.0
	v_fma_f32 v228, -v208, v216, 1.0
	v_fmac_f32_e32 v216, v228, v216
	v_mul_f32_e32 v228, v217, v216
	v_fma_f32 v229, -v208, v228, v217
	v_fmac_f32_e32 v228, v229, v216
	v_fma_f32 v208, -v208, v228, v217
	v_div_fmas_f32 v208, v208, v216, v228
	v_div_fixup_f32 v208, v208, v187, 1.0
	v_lshlrev_b32_e32 v187, 16, v212
	v_and_b32_e32 v212, 0xffff0000, v212
	v_lshlrev_b32_e32 v216, 16, v213
	v_and_b32_e32 v217, 0xffff0000, v213
	v_lshlrev_b32_e32 v228, 16, v214
	v_and_b32_e32 v229, 0xffff0000, v214
	v_sub_f32_e32 v213, v212, v209
	v_sub_f32_e32 v212, v187, v209
	v_sub_f32_e32 v215, v217, v209
	v_sub_f32_e32 v214, v216, v209
	v_sub_f32_e32 v217, v229, v209
	v_sub_f32_e32 v216, v228, v209
	v_sub_f32_e32 v229, v231, v209
	v_sub_f32_e32 v228, v230, v209
	v_pk_mul_f32 v[214:215], v[208:209], v[214:215] op_sel_hi:[0,1]
	v_pk_mul_f32 v[212:213], v[208:209], v[212:213] op_sel_hi:[0,1]
	v_pk_mul_f32 v[228:229], v[208:209], v[228:229] op_sel_hi:[0,1]
	v_pk_mul_f32 v[216:217], v[208:209], v[216:217] op_sel_hi:[0,1]
	v_pk_fma_f32 v[212:213], v[136:137], v[212:213], v[140:141]
	v_pk_fma_f32 v[214:215], v[138:139], v[214:215], v[142:143]
	v_pk_fma_f32 v[216:217], v[128:129], v[216:217], v[132:133]
	v_pk_fma_f32 v[228:229], v[130:131], v[228:229], v[134:135]
	v_pk_fma_f32 v[94:95], v[214:215], s[34:35], v[94:95] op_sel_hi:[1,0,1]
	v_pk_fma_f32 v[92:93], v[212:213], s[34:35], v[92:93] op_sel_hi:[1,0,1]
	v_pk_fma_f32 v[90:91], v[228:229], s[34:35], v[90:91] op_sel_hi:[1,0,1]
	v_pk_fma_f32 v[88:89], v[216:217], s[34:35], v[88:89] op_sel_hi:[1,0,1]
	v_cvt_pk_bf16_f32 v212, v92, v93
	v_cvt_pk_bf16_f32 v213, v94, v95
	v_cvt_pk_bf16_f32 v214, v88, v89
	v_cvt_pk_bf16_f32 v215, v90, v91
	global_store_dwordx4 v[202:203], v[212:215], off
	global_load_dwordx4 v[228:231], v[206:207], off
	s_waitcnt vmcnt(0)
	v_lshlrev_b32_e32 v216, 16, v230
	v_pk_mul_f32 v[214:215], v[210:211], s[30:31] op_sel:[1,0] op_sel_hi:[0,0]
	v_fma_f32 v187, -v215, v215, v214
	v_max_f32_e32 v187, 0, v187
	v_add_f32_e32 v187, 0x3727c5ac, v187
	v_mul_f32_e32 v210, 0x4f800000, v187
	v_cmp_gt_f32_e32 vcc, s61, v187
	v_and_b32_e32 v217, 0xffff0000, v230
	v_sub_f32_e32 v217, v217, v215
	v_cndmask_b32_e32 v187, v187, v210, vcc
	v_sqrt_f32_e32 v210, v187
	v_sub_f32_e32 v216, v216, v215
	v_add_u32_e32 v211, -1, v210
	v_add_u32_e32 v212, 1, v210
	v_fma_f32 v213, -v211, v210, v187
	v_fma_f32 v214, -v212, v210, v187
	v_cmp_ge_f32_e64 s[0:1], 0, v213
	s_nop 1
	v_cndmask_b32_e64 v210, v210, v211, s[0:1]
	v_cmp_lt_f32_e64 s[0:1], 0, v214
	s_nop 1
	v_cndmask_b32_e64 v210, v210, v212, s[0:1]
	v_mul_f32_e32 v211, 0x37800000, v210
	v_cndmask_b32_e32 v210, v210, v211, vcc
	v_cmp_class_f32_e32 vcc, v187, v227
	v_lshl_add_u64 v[212:213], v[184:185], 0, v[178:179]
	s_nop 0
	v_cndmask_b32_e32 v187, v210, v187, vcc
	v_div_scale_f32 v210, s[0:1], v187, v187, 1.0
	v_rcp_f32_e32 v211, v210
	v_div_scale_f32 v184, vcc, 1.0, v187, 1.0
	v_fma_f32 v185, -v210, v211, 1.0
	v_fmac_f32_e32 v211, v185, v211
	v_mul_f32_e32 v185, v184, v211
	v_fma_f32 v214, -v210, v185, v184
	v_fmac_f32_e32 v185, v214, v211
	v_fma_f32 v184, -v210, v185, v184
	v_div_fmas_f32 v184, v184, v211, v185
	v_div_fixup_f32 v214, v184, v187, 1.0
	v_lshlrev_b32_e32 v184, 16, v228
	v_and_b32_e32 v185, 0xffff0000, v228
	v_lshlrev_b32_e32 v187, 16, v229
	v_and_b32_e32 v210, 0xffff0000, v229
	v_lshlrev_b32_e32 v228, 16, v231
	v_and_b32_e32 v229, 0xffff0000, v231
	v_sub_f32_e32 v185, v185, v215
	v_sub_f32_e32 v184, v184, v215
	v_sub_f32_e32 v211, v210, v215
	v_sub_f32_e32 v210, v187, v215
	v_sub_f32_e32 v229, v229, v215
	v_sub_f32_e32 v228, v228, v215
	v_pk_mul_f32 v[210:211], v[214:215], v[210:211] op_sel_hi:[0,1]
	v_pk_mul_f32 v[184:185], v[214:215], v[184:185] op_sel_hi:[0,1]
	v_pk_mul_f32 v[228:229], v[214:215], v[228:229] op_sel_hi:[0,1]
	v_pk_mul_f32 v[216:217], v[214:215], v[216:217] op_sel_hi:[0,1]
	v_pk_fma_f32 v[184:185], v[136:137], v[184:185], v[140:141]
	v_pk_fma_f32 v[210:211], v[138:139], v[210:211], v[142:143]
	v_pk_fma_f32 v[216:217], v[128:129], v[216:217], v[132:133]
	v_pk_fma_f32 v[228:229], v[130:131], v[228:229], v[134:135]
	v_pk_fma_f32 v[86:87], v[210:211], s[34:35], v[86:87] op_sel_hi:[1,0,1]
	v_pk_fma_f32 v[84:85], v[184:185], s[34:35], v[84:85] op_sel_hi:[1,0,1]
	v_pk_fma_f32 v[82:83], v[228:229], s[34:35], v[82:83] op_sel_hi:[1,0,1]
	v_pk_fma_f32 v[80:81], v[216:217], s[34:35], v[80:81] op_sel_hi:[1,0,1]
	v_cvt_pk_bf16_f32 v228, v84, v85
	v_cvt_pk_bf16_f32 v229, v86, v87
	v_cvt_pk_bf16_f32 v230, v80, v81
	v_cvt_pk_bf16_f32 v231, v82, v83
	global_store_dwordx4 v[206:207], v[228:231], off
	global_load_dwordx4 v[228:231], v[212:213], off
	v_pk_mul_f32 v[216:217], v[182:183], s[30:31] op_sel:[1,0] op_sel_hi:[0,0]
	v_fma_f32 v182, -v217, v217, v216
	v_max_f32_e32 v182, 0, v182
	v_add_f32_e32 v182, 0x3727c5ac, v182
	v_mul_f32_e32 v183, 0x4f800000, v182
	v_cmp_gt_f32_e32 vcc, s61, v182
	s_nop 1
	v_cndmask_b32_e32 v182, v182, v183, vcc
	v_sqrt_f32_e32 v183, v182
	s_nop 0
	v_add_u32_e32 v184, -1, v183
	v_add_u32_e32 v185, 1, v183
	v_fma_f32 v187, -v184, v183, v182
	v_fma_f32 v210, -v185, v183, v182
	v_cmp_ge_f32_e64 s[0:1], 0, v187
	s_nop 1
	v_cndmask_b32_e64 v183, v183, v184, s[0:1]
	v_cmp_lt_f32_e64 s[0:1], 0, v210
	v_lshl_add_u64 v[210:211], v[180:181], 0, v[178:179]
	s_waitcnt vmcnt(0)
	v_and_b32_e32 v181, 0xffff0000, v229
	v_cndmask_b32_e64 v183, v183, v185, s[0:1]
	v_mul_f32_e32 v184, 0x37800000, v183
	v_cndmask_b32_e32 v183, v183, v184, vcc
	v_cmp_class_f32_e32 vcc, v182, v227
	v_and_b32_e32 v185, 0xffff0000, v231
	v_sub_f32_e32 v181, v181, v217
	v_cndmask_b32_e32 v182, v183, v182, vcc
	v_div_scale_f32 v183, s[0:1], v182, v182, 1.0
	v_rcp_f32_e32 v184, v183
	v_div_scale_f32 v178, vcc, 1.0, v182, 1.0
	v_sub_f32_e32 v185, v185, v217
	v_fma_f32 v179, -v183, v184, 1.0
	v_fmac_f32_e32 v184, v179, v184
	v_mul_f32_e32 v179, v178, v184
	v_fma_f32 v180, -v183, v179, v178
	v_fmac_f32_e32 v179, v180, v184
	v_fma_f32 v178, -v183, v179, v178
	v_div_fmas_f32 v178, v178, v184, v179
	v_div_fixup_f32 v216, v178, v182, 1.0
	v_lshlrev_b32_e32 v178, 16, v228
	v_and_b32_e32 v179, 0xffff0000, v228
	v_lshlrev_b32_e32 v180, 16, v229
	v_lshlrev_b32_e32 v182, 16, v230
	v_and_b32_e32 v183, 0xffff0000, v230
	v_lshlrev_b32_e32 v184, 16, v231
	v_sub_f32_e32 v179, v179, v217
	v_sub_f32_e32 v178, v178, v217
	v_sub_f32_e32 v180, v180, v217
	v_sub_f32_e32 v183, v183, v217
	v_sub_f32_e32 v182, v182, v217
	v_sub_f32_e32 v184, v184, v217
	v_pk_mul_f32 v[180:181], v[216:217], v[180:181] op_sel_hi:[0,1]
	v_pk_mul_f32 v[178:179], v[216:217], v[178:179] op_sel_hi:[0,1]
	v_pk_mul_f32 v[184:185], v[216:217], v[184:185] op_sel_hi:[0,1]
	v_pk_mul_f32 v[182:183], v[216:217], v[182:183] op_sel_hi:[0,1]
	v_pk_fma_f32 v[178:179], v[136:137], v[178:179], v[140:141]
	v_pk_fma_f32 v[180:181], v[138:139], v[180:181], v[142:143]
	v_pk_fma_f32 v[228:229], v[128:129], v[182:183], v[132:133]
	v_pk_fma_f32 v[230:231], v[130:131], v[184:185], v[134:135]
	v_pk_fma_f32 v[182:183], v[180:181], s[34:35], v[78:79] op_sel_hi:[1,0,1]
	v_pk_fma_f32 v[184:185], v[178:179], s[34:35], v[76:77] op_sel_hi:[1,0,1]
	v_pk_fma_f32 v[178:179], v[230:231], s[34:35], v[74:75] op_sel_hi:[1,0,1]
	v_pk_fma_f32 v[180:181], v[228:229], s[34:35], v[72:73] op_sel_hi:[1,0,1]
	v_cvt_pk_bf16_f32 v72, v184, v185
	v_cvt_pk_bf16_f32 v73, v182, v183
	v_cvt_pk_bf16_f32 v74, v180, v181
	v_cvt_pk_bf16_f32 v75, v178, v179
	global_store_dwordx4 v[212:213], v[72:75], off
	global_load_dwordx4 v[72:75], v[210:211], off
	v_fma_f32 v76, -v201, v201, v200
	v_max_f32_e32 v76, 0, v76
	v_add_f32_e32 v76, 0x3727c5ac, v76
	v_mul_f32_e32 v77, 0x4f800000, v76
	v_cmp_gt_f32_e32 vcc, s61, v76
	s_waitcnt vmcnt(0)
	v_lshlrev_b32_e32 v228, 16, v75
	v_cndmask_b32_e32 v76, v76, v77, vcc
	v_sqrt_f32_e32 v77, v76
	v_and_b32_e32 v229, 0xffff0000, v75
	v_add_u32_e32 v78, -1, v77
	v_add_u32_e32 v79, 1, v77
	v_fma_f32 v187, -v78, v77, v76
	v_fma_f32 v200, -v79, v77, v76
	v_cmp_ge_f32_e64 s[0:1], 0, v187
	s_nop 1
	v_cndmask_b32_e64 v77, v77, v78, s[0:1]
	v_cmp_lt_f32_e64 s[0:1], 0, v200
	s_nop 1
	v_cndmask_b32_e64 v77, v77, v79, s[0:1]
	v_mul_f32_e32 v78, 0x37800000, v77
	v_cndmask_b32_e32 v77, v77, v78, vcc
	v_cmp_class_f32_e32 vcc, v76, v227
	s_nop 1
	v_cndmask_b32_e32 v76, v77, v76, vcc
	v_div_scale_f32 v77, s[0:1], v76, v76, 1.0
	v_rcp_f32_e32 v78, v77
	v_div_scale_f32 v79, vcc, 1.0, v76, 1.0
	v_fma_f32 v187, -v77, v78, 1.0
	v_fmac_f32_e32 v78, v187, v78
	v_mul_f32_e32 v187, v79, v78
	v_fma_f32 v200, -v77, v187, v79
	v_fmac_f32_e32 v187, v200, v78
	v_fma_f32 v77, -v77, v187, v79
	v_div_fmas_f32 v77, v77, v78, v187
	v_div_fixup_f32 v200, v77, v76, 1.0
	v_lshlrev_b32_e32 v76, 16, v72
	v_and_b32_e32 v72, 0xffff0000, v72
	v_lshlrev_b32_e32 v77, 16, v73
	v_and_b32_e32 v78, 0xffff0000, v73
	v_lshlrev_b32_e32 v79, 16, v74
	v_and_b32_e32 v187, 0xffff0000, v74
	v_sub_f32_e32 v73, v72, v201
	v_sub_f32_e32 v72, v76, v201
	v_sub_f32_e32 v75, v78, v201
	v_sub_f32_e32 v74, v77, v201
	v_sub_f32_e32 v77, v187, v201
	v_sub_f32_e32 v76, v79, v201
	v_sub_f32_e32 v79, v229, v201
	v_sub_f32_e32 v78, v228, v201
	v_pk_mul_f32 v[74:75], v[200:201], v[74:75] op_sel_hi:[0,1]
	v_pk_mul_f32 v[72:73], v[200:201], v[72:73] op_sel_hi:[0,1]
	v_pk_mul_f32 v[78:79], v[200:201], v[78:79] op_sel_hi:[0,1]
	v_pk_mul_f32 v[76:77], v[200:201], v[76:77] op_sel_hi:[0,1]
	v_pk_fma_f32 v[72:73], v[136:137], v[72:73], v[140:141]
	v_pk_fma_f32 v[74:75], v[138:139], v[74:75], v[142:143]
	v_pk_fma_f32 v[76:77], v[128:129], v[76:77], v[132:133]
	v_pk_fma_f32 v[78:79], v[130:131], v[78:79], v[134:135]
	v_pk_fma_f32 v[130:131], v[74:75], s[34:35], v[70:71] op_sel_hi:[1,0,1]
	v_pk_fma_f32 v[134:135], v[72:73], s[34:35], v[68:69] op_sel_hi:[1,0,1]
	v_pk_fma_f32 v[128:129], v[78:79], s[34:35], v[66:67] op_sel_hi:[1,0,1]
	v_pk_fma_f32 v[132:133], v[76:77], s[34:35], v[64:65] op_sel_hi:[1,0,1]
	v_cvt_pk_bf16_f32 v64, v134, v135
	v_cvt_pk_bf16_f32 v65, v130, v131
	v_cvt_pk_bf16_f32 v66, v132, v133
	v_cvt_pk_bf16_f32 v67, v128, v129
	global_store_dwordx4 v[210:211], v[64:67], off
	global_load_dwordx4 v[136:139], v[176:177], off offset:256
	s_waitcnt vmcnt(0)
	v_lshlrev_b32_e32 v140, 16, v136
	v_or_b32_e32 v64, 0x80, v186
	v_ashrrev_i32_e32 v65, 31, v64
	v_lshlrev_b64 v[64:65], 2, v[64:65]
	v_lshl_add_u64 v[66:67], s[14:15], 0, v[64:65]
	v_lshl_add_u64 v[76:77], s[20:21], 0, v[64:65]
	global_load_dwordx4 v[68:71], v[76:77], off
	global_load_dwordx4 v[72:75], v[66:67], off
	s_nop 0
	global_load_dwordx4 v[64:67], v[66:67], off offset:16
	s_nop 0
	global_load_dwordx4 v[76:79], v[76:77], off offset:16
	v_and_b32_e32 v136, 0xffff0000, v136
	v_lshlrev_b32_e32 v141, 16, v137
	v_and_b32_e32 v142, 0xffff0000, v137
	v_lshlrev_b32_e32 v143, 16, v138
	v_and_b32_e32 v186, 0xffff0000, v138
	v_lshlrev_b32_e32 v187, 16, v139
	v_and_b32_e32 v228, 0xffff0000, v139
	v_sub_f32_e32 v137, v136, v189
	v_sub_f32_e32 v136, v140, v189
	v_sub_f32_e32 v139, v142, v189
	v_sub_f32_e32 v138, v141, v189
	v_sub_f32_e32 v141, v186, v189
	v_sub_f32_e32 v140, v143, v189
	v_sub_f32_e32 v143, v228, v189
	v_sub_f32_e32 v142, v187, v189
	v_pk_mul_f32 v[138:139], v[188:189], v[138:139] op_sel_hi:[0,1]
	v_pk_mul_f32 v[136:137], v[188:189], v[136:137] op_sel_hi:[0,1]
	v_pk_mul_f32 v[142:143], v[188:189], v[142:143] op_sel_hi:[0,1]
	v_pk_mul_f32 v[140:141], v[188:189], v[140:141] op_sel_hi:[0,1]
	s_waitcnt vmcnt(0)
	v_pk_fma_f32 v[136:137], v[72:73], v[136:137], v[68:69]
	v_pk_fma_f32 v[138:139], v[74:75], v[138:139], v[70:71]
	v_pk_fma_f32 v[140:141], v[64:65], v[140:141], v[76:77]
	v_pk_fma_f32 v[142:143], v[66:67], v[142:143], v[78:79]
	v_pk_fma_f32 v[62:63], v[138:139], s[34:35], v[62:63] op_sel_hi:[1,0,1]
	v_pk_fma_f32 v[60:61], v[136:137], s[34:35], v[60:61] op_sel_hi:[1,0,1]
	v_pk_fma_f32 v[58:59], v[142:143], s[34:35], v[58:59] op_sel_hi:[1,0,1]
	v_pk_fma_f32 v[56:57], v[140:141], s[34:35], v[56:57] op_sel_hi:[1,0,1]
	v_cvt_pk_bf16_f32 v136, v60, v61
	v_cvt_pk_bf16_f32 v137, v62, v63
	v_cvt_pk_bf16_f32 v138, v56, v57
	v_cvt_pk_bf16_f32 v139, v58, v59
	global_store_dwordx4 v[176:177], v[136:139], off offset:256
	global_load_dwordx4 v[244:247], v[190:191], off offset:256
	global_load_dwordx4 v[240:243], v[192:193], off offset:256
	s_nop 0
	s_waitcnt vmcnt(1)
	v_lshlrev_b32_e32 v140, 16, v244
	v_and_b32_e32 v136, 0xffff0000, v244
	v_lshlrev_b32_e32 v141, 16, v245
	v_and_b32_e32 v142, 0xffff0000, v245
	v_lshlrev_b32_e32 v143, 16, v246
	v_and_b32_e32 v176, 0xffff0000, v246
	v_lshlrev_b32_e32 v177, 16, v247
	v_and_b32_e32 v186, 0xffff0000, v247
	v_sub_f32_e32 v137, v136, v195
	v_sub_f32_e32 v136, v140, v195
	v_sub_f32_e32 v139, v142, v195
	v_sub_f32_e32 v138, v141, v195
	v_sub_f32_e32 v141, v176, v195
	v_sub_f32_e32 v140, v143, v195
	v_sub_f32_e32 v143, v186, v195
	v_sub_f32_e32 v142, v177, v195
	v_pk_mul_f32 v[138:139], v[194:195], v[138:139] op_sel_hi:[0,1]
	v_pk_mul_f32 v[136:137], v[194:195], v[136:137] op_sel_hi:[0,1]
	v_pk_mul_f32 v[142:143], v[194:195], v[142:143] op_sel_hi:[0,1]
	v_pk_mul_f32 v[140:141], v[194:195], v[140:141] op_sel_hi:[0,1]
	v_pk_fma_f32 v[136:137], v[72:73], v[136:137], v[68:69]
	v_pk_fma_f32 v[138:139], v[74:75], v[138:139], v[70:71]
	v_pk_fma_f32 v[140:141], v[64:65], v[140:141], v[76:77]
	v_pk_fma_f32 v[142:143], v[66:67], v[142:143], v[78:79]
	v_pk_fma_f32 v[54:55], v[138:139], s[34:35], v[54:55] op_sel_hi:[1,0,1]
	v_pk_fma_f32 v[52:53], v[136:137], s[34:35], v[52:53] op_sel_hi:[1,0,1]
	v_pk_fma_f32 v[50:51], v[142:143], s[34:35], v[50:51] op_sel_hi:[1,0,1]
	v_pk_fma_f32 v[48:49], v[140:141], s[34:35], v[48:49] op_sel_hi:[1,0,1]
	v_cvt_pk_bf16_f32 v136, v52, v53
	v_cvt_pk_bf16_f32 v137, v54, v55
	v_cvt_pk_bf16_f32 v138, v48, v49
	v_cvt_pk_bf16_f32 v139, v50, v51
	global_store_dwordx4 v[190:191], v[136:139], off offset:256
	global_load_dwordx4 v[244:247], v[196:197], off offset:256
	s_nop 0
	s_waitcnt vmcnt(2)
	v_lshlrev_b32_e32 v140, 16, v240
	v_and_b32_e32 v136, 0xffff0000, v240
	v_lshlrev_b32_e32 v141, 16, v241
	v_and_b32_e32 v142, 0xffff0000, v241
	v_lshlrev_b32_e32 v143, 16, v242
	v_and_b32_e32 v176, 0xffff0000, v242
	v_lshlrev_b32_e32 v177, 16, v243
	v_and_b32_e32 v186, 0xffff0000, v243
	v_sub_f32_e32 v137, v136, v199
	v_sub_f32_e32 v136, v140, v199
	v_sub_f32_e32 v139, v142, v199
	v_sub_f32_e32 v138, v141, v199
	v_sub_f32_e32 v141, v176, v199
	v_sub_f32_e32 v140, v143, v199
	v_sub_f32_e32 v143, v186, v199
	v_sub_f32_e32 v142, v177, v199
	v_pk_mul_f32 v[138:139], v[198:199], v[138:139] op_sel_hi:[0,1]
	v_pk_mul_f32 v[136:137], v[198:199], v[136:137] op_sel_hi:[0,1]
	v_pk_mul_f32 v[142:143], v[198:199], v[142:143] op_sel_hi:[0,1]
	v_pk_mul_f32 v[140:141], v[198:199], v[140:141] op_sel_hi:[0,1]
	v_pk_fma_f32 v[136:137], v[72:73], v[136:137], v[68:69]
	v_pk_fma_f32 v[138:139], v[74:75], v[138:139], v[70:71]
	v_pk_fma_f32 v[140:141], v[64:65], v[140:141], v[76:77]
	v_pk_fma_f32 v[142:143], v[66:67], v[142:143], v[78:79]
	v_pk_fma_f32 v[46:47], v[138:139], s[34:35], v[46:47] op_sel_hi:[1,0,1]
	v_pk_fma_f32 v[44:45], v[136:137], s[34:35], v[44:45] op_sel_hi:[1,0,1]
	v_pk_fma_f32 v[42:43], v[142:143], s[34:35], v[42:43] op_sel_hi:[1,0,1]
	v_pk_fma_f32 v[40:41], v[140:141], s[34:35], v[40:41] op_sel_hi:[1,0,1]
	v_cvt_pk_bf16_f32 v136, v44, v45
	v_cvt_pk_bf16_f32 v137, v46, v47
	v_cvt_pk_bf16_f32 v138, v40, v41
	v_cvt_pk_bf16_f32 v139, v42, v43
	global_store_dwordx4 v[192:193], v[136:139], off offset:256
	global_load_dwordx4 v[240:243], v[202:203], off offset:256
	s_nop 0
	s_waitcnt vmcnt(2)
	v_lshlrev_b32_e32 v140, 16, v244
	v_and_b32_e32 v136, 0xffff0000, v244
	v_lshlrev_b32_e32 v141, 16, v245
	v_and_b32_e32 v142, 0xffff0000, v245
	v_lshlrev_b32_e32 v143, 16, v246
	v_and_b32_e32 v176, 0xffff0000, v246
	v_lshlrev_b32_e32 v177, 16, v247
	v_and_b32_e32 v186, 0xffff0000, v247
	v_sub_f32_e32 v137, v136, v205
	v_sub_f32_e32 v136, v140, v205
	v_sub_f32_e32 v139, v142, v205
	v_sub_f32_e32 v138, v141, v205
	v_sub_f32_e32 v141, v176, v205
	v_sub_f32_e32 v140, v143, v205
	v_sub_f32_e32 v143, v186, v205
	v_sub_f32_e32 v142, v177, v205
	v_pk_mul_f32 v[138:139], v[204:205], v[138:139] op_sel_hi:[0,1]
	v_pk_mul_f32 v[136:137], v[204:205], v[136:137] op_sel_hi:[0,1]
	v_pk_mul_f32 v[142:143], v[204:205], v[142:143] op_sel_hi:[0,1]
	v_pk_mul_f32 v[140:141], v[204:205], v[140:141] op_sel_hi:[0,1]
	v_pk_fma_f32 v[136:137], v[72:73], v[136:137], v[68:69]
	v_pk_fma_f32 v[138:139], v[74:75], v[138:139], v[70:71]
	v_pk_fma_f32 v[140:141], v[64:65], v[140:141], v[76:77]
	v_pk_fma_f32 v[142:143], v[66:67], v[142:143], v[78:79]
	v_pk_fma_f32 v[38:39], v[138:139], s[34:35], v[38:39] op_sel_hi:[1,0,1]
	v_pk_fma_f32 v[36:37], v[136:137], s[34:35], v[36:37] op_sel_hi:[1,0,1]
	v_pk_fma_f32 v[34:35], v[142:143], s[34:35], v[34:35] op_sel_hi:[1,0,1]
	v_pk_fma_f32 v[32:33], v[140:141], s[34:35], v[32:33] op_sel_hi:[1,0,1]
	v_cvt_pk_bf16_f32 v136, v36, v37
	v_cvt_pk_bf16_f32 v137, v38, v39
	v_cvt_pk_bf16_f32 v138, v32, v33
	v_cvt_pk_bf16_f32 v139, v34, v35
	global_store_dwordx4 v[196:197], v[136:139], off offset:256
	global_load_dwordx4 v[244:247], v[206:207], off offset:256
	s_nop 0
	s_waitcnt vmcnt(2)
	v_lshlrev_b32_e32 v140, 16, v240
	v_and_b32_e32 v136, 0xffff0000, v240
	v_lshlrev_b32_e32 v141, 16, v241
	v_and_b32_e32 v142, 0xffff0000, v241
	v_lshlrev_b32_e32 v143, 16, v242
	v_and_b32_e32 v176, 0xffff0000, v242
	v_lshlrev_b32_e32 v177, 16, v243
	v_and_b32_e32 v186, 0xffff0000, v243
	v_sub_f32_e32 v137, v136, v209
	v_sub_f32_e32 v136, v140, v209
	v_sub_f32_e32 v139, v142, v209
	v_sub_f32_e32 v138, v141, v209
	v_sub_f32_e32 v141, v176, v209
	v_sub_f32_e32 v140, v143, v209
	v_sub_f32_e32 v143, v186, v209
	v_sub_f32_e32 v142, v177, v209
	v_pk_mul_f32 v[138:139], v[208:209], v[138:139] op_sel_hi:[0,1]
	v_pk_mul_f32 v[136:137], v[208:209], v[136:137] op_sel_hi:[0,1]
	v_pk_mul_f32 v[142:143], v[208:209], v[142:143] op_sel_hi:[0,1]
	v_pk_mul_f32 v[140:141], v[208:209], v[140:141] op_sel_hi:[0,1]
	v_pk_fma_f32 v[136:137], v[72:73], v[136:137], v[68:69]
	v_pk_fma_f32 v[138:139], v[74:75], v[138:139], v[70:71]
	v_pk_fma_f32 v[140:141], v[64:65], v[140:141], v[76:77]
	v_pk_fma_f32 v[142:143], v[66:67], v[142:143], v[78:79]
	v_pk_fma_f32 v[30:31], v[138:139], s[34:35], v[30:31] op_sel_hi:[1,0,1]
	v_pk_fma_f32 v[28:29], v[136:137], s[34:35], v[28:29] op_sel_hi:[1,0,1]
	v_pk_fma_f32 v[26:27], v[142:143], s[34:35], v[26:27] op_sel_hi:[1,0,1]
	v_pk_fma_f32 v[24:25], v[140:141], s[34:35], v[24:25] op_sel_hi:[1,0,1]
	v_cvt_pk_bf16_f32 v136, v28, v29
	v_cvt_pk_bf16_f32 v137, v30, v31
	v_cvt_pk_bf16_f32 v138, v24, v25
	v_cvt_pk_bf16_f32 v139, v26, v27
	global_store_dwordx4 v[202:203], v[136:139], off offset:256
	global_load_dwordx4 v[240:243], v[212:213], off offset:256
	s_nop 0
	s_waitcnt vmcnt(2)
	v_lshlrev_b32_e32 v140, 16, v244
	v_and_b32_e32 v136, 0xffff0000, v244
	v_lshlrev_b32_e32 v141, 16, v245
	v_and_b32_e32 v142, 0xffff0000, v245
	v_lshlrev_b32_e32 v143, 16, v246
	v_and_b32_e32 v176, 0xffff0000, v246
	v_lshlrev_b32_e32 v177, 16, v247
	v_and_b32_e32 v186, 0xffff0000, v247
	v_sub_f32_e32 v137, v136, v215
	v_sub_f32_e32 v136, v140, v215
	v_sub_f32_e32 v139, v142, v215
	v_sub_f32_e32 v138, v141, v215
	v_sub_f32_e32 v141, v176, v215
	v_sub_f32_e32 v140, v143, v215
	v_sub_f32_e32 v143, v186, v215
	v_sub_f32_e32 v142, v177, v215
	v_pk_mul_f32 v[138:139], v[214:215], v[138:139] op_sel_hi:[0,1]
	v_pk_mul_f32 v[136:137], v[214:215], v[136:137] op_sel_hi:[0,1]
	v_pk_mul_f32 v[142:143], v[214:215], v[142:143] op_sel_hi:[0,1]
	v_pk_mul_f32 v[140:141], v[214:215], v[140:141] op_sel_hi:[0,1]
	v_pk_fma_f32 v[136:137], v[72:73], v[136:137], v[68:69]
	v_pk_fma_f32 v[138:139], v[74:75], v[138:139], v[70:71]
	v_pk_fma_f32 v[140:141], v[64:65], v[140:141], v[76:77]
	v_pk_fma_f32 v[142:143], v[66:67], v[142:143], v[78:79]
	v_pk_fma_f32 v[22:23], v[138:139], s[34:35], v[22:23] op_sel_hi:[1,0,1]
	v_pk_fma_f32 v[20:21], v[136:137], s[34:35], v[20:21] op_sel_hi:[1,0,1]
	v_pk_fma_f32 v[18:19], v[142:143], s[34:35], v[18:19] op_sel_hi:[1,0,1]
	v_pk_fma_f32 v[16:17], v[140:141], s[34:35], v[16:17] op_sel_hi:[1,0,1]
	v_cvt_pk_bf16_f32 v136, v20, v21
	v_cvt_pk_bf16_f32 v137, v22, v23
	v_cvt_pk_bf16_f32 v138, v16, v17
	v_cvt_pk_bf16_f32 v139, v18, v19
	global_store_dwordx4 v[206:207], v[136:139], off offset:256
	s_nop 0
	s_waitcnt vmcnt(1)
	v_lshlrev_b32_e32 v140, 16, v240
	v_and_b32_e32 v136, 0xffff0000, v240
	v_lshlrev_b32_e32 v141, 16, v241
	v_and_b32_e32 v142, 0xffff0000, v241
	v_lshlrev_b32_e32 v143, 16, v242
	v_and_b32_e32 v176, 0xffff0000, v242
	v_lshlrev_b32_e32 v177, 16, v243
	v_and_b32_e32 v186, 0xffff0000, v243
	v_sub_f32_e32 v137, v136, v217
	v_sub_f32_e32 v136, v140, v217
	v_sub_f32_e32 v139, v142, v217
	v_sub_f32_e32 v138, v141, v217
	v_sub_f32_e32 v141, v176, v217
	v_sub_f32_e32 v140, v143, v217
	v_sub_f32_e32 v143, v186, v217
	v_sub_f32_e32 v142, v177, v217
	v_pk_mul_f32 v[138:139], v[216:217], v[138:139] op_sel_hi:[0,1]
	v_pk_mul_f32 v[136:137], v[216:217], v[136:137] op_sel_hi:[0,1]
	v_pk_mul_f32 v[142:143], v[216:217], v[142:143] op_sel_hi:[0,1]
	v_pk_mul_f32 v[140:141], v[216:217], v[140:141] op_sel_hi:[0,1]
	v_pk_fma_f32 v[136:137], v[72:73], v[136:137], v[68:69]
	v_pk_fma_f32 v[138:139], v[74:75], v[138:139], v[70:71]
	v_pk_fma_f32 v[140:141], v[64:65], v[140:141], v[76:77]
	v_pk_fma_f32 v[142:143], v[66:67], v[142:143], v[78:79]
	v_pk_fma_f32 v[14:15], v[138:139], s[34:35], v[14:15] op_sel_hi:[1,0,1]
	v_pk_fma_f32 v[12:13], v[136:137], s[34:35], v[12:13] op_sel_hi:[1,0,1]
	v_pk_fma_f32 v[10:11], v[142:143], s[34:35], v[10:11] op_sel_hi:[1,0,1]
	v_pk_fma_f32 v[8:9], v[140:141], s[34:35], v[8:9] op_sel_hi:[1,0,1]
	v_cvt_pk_bf16_f32 v136, v12, v13
	v_cvt_pk_bf16_f32 v137, v14, v15
	v_cvt_pk_bf16_f32 v138, v8, v9
	v_cvt_pk_bf16_f32 v139, v10, v11
	global_store_dwordx4 v[212:213], v[136:139], off offset:256
	global_load_dwordx4 v[136:139], v[210:211], off offset:256
	v_add_f32_e32 v140, v124, v125
	v_add_f32_e32 v141, v126, v127
	v_add_f32_e32 v142, v120, v121
	v_add_f32_e32 v143, v122, v123
	v_mul_f32_e32 v125, v125, v125
	v_mul_f32_e32 v127, v127, v127
	v_mul_f32_e32 v121, v121, v121
	v_mul_f32_e32 v123, v123, v123
	v_fmac_f32_e32 v125, v124, v124
	v_fmac_f32_e32 v127, v126, v126
	v_fmac_f32_e32 v121, v120, v120
	v_fmac_f32_e32 v123, v122, v122
	v_add_f32_e32 v122, v125, v127
	v_add_f32_e32 v121, v121, v123
	v_add_f32_e32 v121, v122, v121
	v_add_f32_e32 v122, v60, v61
	v_add_f32_e32 v123, v62, v63
	v_add_f32_e32 v124, v56, v57
	v_add_f32_e32 v125, v58, v59
	v_mul_f32_e32 v61, v61, v61
	v_mul_f32_e32 v63, v63, v63
	v_mul_f32_e32 v57, v57, v57
	v_mul_f32_e32 v59, v59, v59
	v_add_f32_e32 v140, v140, v141
	v_add_f32_e32 v141, v142, v143
	v_fmac_f32_e32 v61, v60, v60
	v_fmac_f32_e32 v63, v62, v62
	v_fmac_f32_e32 v57, v56, v56
	v_fmac_f32_e32 v59, v58, v58
	v_add_f32_e32 v120, v140, v141
	v_add_f32_e32 v122, v122, v123
	v_add_f32_e32 v123, v124, v125
	v_add_f32_e32 v58, v61, v63
	v_add_f32_e32 v57, v57, v59
	v_add_f32_e32 v120, 0, v120
	v_add_f32_e32 v56, v122, v123
	v_add_f32_e32 v57, v58, v57
	v_add_f32_e32 v56, v120, v56
	v_add_f32_e32 v59, v121, v57
	ds_bpermute_b32 v58, v222, v56
	ds_bpermute_b32 v60, v222, v59
	s_waitcnt lgkmcnt(0)
	v_add_f32_e32 v56, v56, v58
	v_add_f32_e32 v58, v59, v60
	ds_bpermute_b32 v57, v221, v56
	s_waitcnt vmcnt(0)
	v_lshlrev_b32_e32 v59, 16, v136
	v_and_b32_e32 v60, 0xffff0000, v136
	v_lshlrev_b32_e32 v62, 16, v137
	v_and_b32_e32 v63, 0xffff0000, v137
	v_lshlrev_b32_e32 v120, 16, v138
	v_and_b32_e32 v121, 0xffff0000, v138
	v_lshlrev_b32_e32 v122, 16, v139
	v_and_b32_e32 v123, 0xffff0000, v139
	v_sub_f32_e32 v61, v60, v201
	v_sub_f32_e32 v60, v59, v201
	v_sub_f32_e32 v63, v63, v201
	v_sub_f32_e32 v62, v62, v201
	v_sub_f32_e32 v121, v121, v201
	v_sub_f32_e32 v120, v120, v201
	v_sub_f32_e32 v123, v123, v201
	v_sub_f32_e32 v122, v122, v201
	v_pk_mul_f32 v[62:63], v[200:201], v[62:63] op_sel_hi:[0,1]
	v_pk_mul_f32 v[60:61], v[200:201], v[60:61] op_sel_hi:[0,1]
	v_pk_mul_f32 v[122:123], v[200:201], v[122:123] op_sel_hi:[0,1]
	v_pk_mul_f32 v[120:121], v[200:201], v[120:121] op_sel_hi:[0,1]
	v_pk_fma_f32 v[60:61], v[72:73], v[60:61], v[68:69]
	v_pk_fma_f32 v[62:63], v[74:75], v[62:63], v[70:71]
	v_pk_fma_f32 v[64:65], v[64:65], v[120:121], v[76:77]
	v_pk_fma_f32 v[66:67], v[66:67], v[122:123], v[78:79]
	v_pk_fma_f32 v[6:7], v[62:63], s[34:35], v[6:7] op_sel_hi:[1,0,1]
	v_pk_fma_f32 v[4:5], v[60:61], s[34:35], v[4:5] op_sel_hi:[1,0,1]
	v_pk_fma_f32 v[2:3], v[66:67], s[34:35], v[2:3] op_sel_hi:[1,0,1]
	v_pk_fma_f32 v[0:1], v[64:65], s[34:35], v[0:1] op_sel_hi:[1,0,1]
	v_cvt_pk_bf16_f32 v60, v4, v5
	v_cvt_pk_bf16_f32 v61, v6, v7
	v_cvt_pk_bf16_f32 v62, v0, v1
	v_cvt_pk_bf16_f32 v63, v2, v3
	ds_bpermute_b32 v59, v221, v58
	global_store_dwordx4 v[210:211], v[60:63], off offset:256
	s_and_saveexec_b64 s[0:1], s[4:5]
	s_cbranch_execz .LBB0_1477
	s_waitcnt lgkmcnt(0)
	v_add_f32_e32 v58, v58, v59
	v_add_f32_e32 v59, v56, v57
	v_lshl_add_u64 v[56:57], s[22:23], 0, v[164:165]
	global_atomic_add_f32 v[56:57], v59, off
	global_atomic_add_f32 v[56:57], v58, off offset:4
